# v032 stack + hand-written EpiResid epilogues with 4-block residual prefetch (XB store dropped in last FFN-down)
# baseline (speedup 1.0000x reference)
; __device__ __forceinline__ unsigned pk(float lo, float hi) { return pg8::cvt_pk_bf16(lo, hi); }
; __device__ __forceinline__ float dot4(f32x4 v) { return (v[0] * v[0] + v[1] * v[1]) + (v[2] * v[2] + v[3] * v[3]); }
;     __device__ __forceinline__ void operator()(const pg8::f32x4 (&acc)[2][2][4][2], const pg8::Unit& u, int wr, int wc, int fr, int fq) const {
;         const int row0 = u.pm * 256 + wr * 64 + fr;
; #pragma unroll
;         for (int ai = 0; ai < 2; ++ai)
; #pragma unroll
;             for (int m = 0; m < 4; ++m) {
;                 const int row = row0 + ai * 128 + m * 16;
;                 const float* xi = (row < MP) ? xin_p + (size_t)row * DM : xin_s + (size_t)(row - MP) * DM;
;                 float sq = 0.f;
; #pragma unroll
;                 for (int bj = 0; bj < 2; ++bj) { const int col = u.pn * 256 + bj * 128 + wc * 32 + 8 * fq;
;                     const f32x4 a0 = *(const f32x4*)(xi + col) + acc[ai][bj][m][0], a1 = *(const f32x4*)(xi + col + 4) + acc[ai][bj][m][1];
;                     *(f32x4*)(xout + (size_t)row * DM + col) = a0; *(f32x4*)(xout + (size_t)row * DM + col + 4) = a1;
;                     u32x4 w; w.x = pk(a0[0], a0[1]); w.y = pk(a0[2], a0[3]); w.z = pk(a1[0], a1[1]); w.w = pk(a1[2], a1[3]);
;                     *(u32x4*)(xb + (size_t)row * DM + col) = w;
;                     sq += dot4(a0) + dot4(a1); }
;                 sq += __shfl_xor(sq, 16); sq += __shfl_xor(sq, 32);
;                 if (fq == 0) atomicAdd(ssout + row, sq);
.LBB0_786:
	s_cmp_lt_u32 s74, 64
	s_cselect_b32 s98, s12, s14
	s_cselect_b32 s99, s13, s15
	s_cselect_b32 s100, 0, 0x4000
	v_lshl_add_u32 v138, s74, 8, v154
	v_lshl_or_b32 v161, s72, 8, v156
	v_lshlrev_b32_e32 v167, 2, v138
	v_lshlrev_b32_e32 v166, 1, v161
	v_lshl_add_u32 v250, v138, 11, v166
	v_lshlrev_b32_e32 v166, 2, v161
	v_lshl_add_u32 v251, v138, 12, v166
	v_subrev_u32_e32 v138, s100, v138
	v_lshl_add_u32 v222, v138, 12, v166
	global_load_dwordx4 v[146:149], v222, s[98:99]
	global_load_dwordx4 v[150:153], v222, s[98:99] offset:16
	global_load_dwordx4 v[162:165], v222, s[98:99] offset:512
	global_load_dwordx4 v[170:173], v222, s[98:99] offset:528
	v_add_u32_e32 v223, 0x10000, v222
	global_load_dwordx4 v[174:177], v223, s[98:99]
	global_load_dwordx4 v[178:181], v223, s[98:99] offset:16
	global_load_dwordx4 v[182:185], v223, s[98:99] offset:512
	global_load_dwordx4 v[186:189], v223, s[98:99] offset:528
	v_add_u32_e32 v223, 0x20000, v222
	global_load_dwordx4 v[190:193], v223, s[98:99]
	global_load_dwordx4 v[194:197], v223, s[98:99] offset:16
	global_load_dwordx4 v[198:201], v223, s[98:99] offset:512
	global_load_dwordx4 v[202:205], v223, s[98:99] offset:528
	v_add_u32_e32 v223, 0x30000, v222
	global_load_dwordx4 v[206:209], v223, s[98:99]
	global_load_dwordx4 v[210:213], v223, s[98:99] offset:16
	global_load_dwordx4 v[214:217], v223, s[98:99] offset:512
	global_load_dwordx4 v[218:221], v223, s[98:99] offset:528
	s_waitcnt vmcnt(12)
	v_pk_add_f32 v[126:127], v[126:127], v[146:147]
	v_pk_add_f32 v[128:129], v[128:129], v[148:149]
	v_pk_add_f32 v[122:123], v[122:123], v[150:151]
	v_pk_add_f32 v[124:125], v[124:125], v[152:153]
	v_pk_add_f32 v[118:119], v[118:119], v[162:163]
	v_pk_add_f32 v[120:121], v[120:121], v[164:165]
	v_pk_add_f32 v[114:115], v[114:115], v[170:171]
	v_pk_add_f32 v[116:117], v[116:117], v[172:173]
	global_store_dwordx4 v251, v[126:129], s[16:17]
	global_store_dwordx4 v251, v[122:125], s[16:17] offset:16
	global_store_dwordx4 v251, v[118:121], s[16:17] offset:512
	global_store_dwordx4 v251, v[114:117], s[16:17] offset:528
	v_cvt_pk_bf16_f32 v146, v126, v127
	v_cvt_pk_bf16_f32 v147, v128, v129
	v_cvt_pk_bf16_f32 v148, v122, v123
	v_cvt_pk_bf16_f32 v149, v124, v125
	v_cvt_pk_bf16_f32 v150, v118, v119
	v_cvt_pk_bf16_f32 v151, v120, v121
	v_cvt_pk_bf16_f32 v152, v114, v115
	v_cvt_pk_bf16_f32 v153, v116, v117
	v_mul_f32_e32 v162, v127, v127
	v_mul_f32_e32 v163, v129, v129
	v_mul_f32_e32 v164, v123, v123
	v_mul_f32_e32 v165, v125, v125
	v_fmac_f32_e32 v162, v126, v126
	v_fmac_f32_e32 v163, v128, v128
	v_fmac_f32_e32 v164, v122, v122
	v_fmac_f32_e32 v165, v124, v124
	v_add_f32_e32 v162, v162, v163
	v_add_f32_e32 v164, v164, v165
	v_add_f32_e32 v225, v162, v164
	v_mul_f32_e32 v162, v119, v119
	v_mul_f32_e32 v163, v121, v121
	v_mul_f32_e32 v164, v115, v115
	v_mul_f32_e32 v165, v117, v117
	v_fmac_f32_e32 v162, v118, v118
	v_fmac_f32_e32 v163, v120, v120
	v_fmac_f32_e32 v164, v114, v114
	v_fmac_f32_e32 v165, v116, v116
	v_add_f32_e32 v162, v162, v163
	v_add_f32_e32 v164, v164, v165
	v_add_f32_e32 v162, v162, v164
	v_add_f32_e32 v225, v225, v162
	global_store_dwordx4 v250, v[146:149], s[64:65]
	global_store_dwordx4 v250, v[150:153], s[64:65] offset:256
	v_mov_b32_e32 v226, v225
	s_nop 1
	v_permlane16_swap_b32_e32 v225, v226
	v_add_f32_e32 v225, v225, v226
	v_mov_b32_e32 v226, v225
	s_nop 1
	v_permlane32_swap_b32_e32 v225, v226
	v_add_f32_e32 v225, v225, v226
	s_mov_b64 exec, s[0:1]
	global_atomic_add_f32 v167, v225, s[10:11]
	s_mov_b64 exec, -1
	v_add_u32_e32 v223, 0x80000, v222
	global_load_dwordx4 v[146:149], v223, s[98:99]
	global_load_dwordx4 v[150:153], v223, s[98:99] offset:16
	global_load_dwordx4 v[162:165], v223, s[98:99] offset:512
	global_load_dwordx4 v[170:173], v223, s[98:99] offset:528
	s_waitcnt vmcnt(12)
	v_pk_add_f32 v[110:111], v[110:111], v[174:175]
	v_pk_add_f32 v[112:113], v[112:113], v[176:177]
	v_pk_add_f32 v[106:107], v[106:107], v[178:179]
	v_pk_add_f32 v[108:109], v[108:109], v[180:181]
	v_pk_add_f32 v[102:103], v[102:103], v[182:183]
	v_pk_add_f32 v[104:105], v[104:105], v[184:185]
	v_pk_add_f32 v[98:99], v[98:99], v[186:187]
	v_pk_add_f32 v[100:101], v[100:101], v[188:189]
	v_add_u32_e32 v224, 0x10000, v251
	global_store_dwordx4 v224, v[110:113], s[16:17]
	global_store_dwordx4 v224, v[106:109], s[16:17] offset:16
	global_store_dwordx4 v224, v[102:105], s[16:17] offset:512
	global_store_dwordx4 v224, v[98:101], s[16:17] offset:528
	v_cvt_pk_bf16_f32 v174, v110, v111
	v_cvt_pk_bf16_f32 v175, v112, v113
	v_cvt_pk_bf16_f32 v176, v106, v107
	v_cvt_pk_bf16_f32 v177, v108, v109
	v_cvt_pk_bf16_f32 v178, v102, v103
	v_cvt_pk_bf16_f32 v179, v104, v105
	v_cvt_pk_bf16_f32 v180, v98, v99
	v_cvt_pk_bf16_f32 v181, v100, v101
	v_mul_f32_e32 v182, v111, v111
	v_mul_f32_e32 v183, v113, v113
	v_mul_f32_e32 v184, v107, v107
	v_mul_f32_e32 v185, v109, v109
	v_fmac_f32_e32 v182, v110, v110
	v_fmac_f32_e32 v183, v112, v112
	v_fmac_f32_e32 v184, v106, v106
	v_fmac_f32_e32 v185, v108, v108
	v_add_f32_e32 v182, v182, v183
	v_add_f32_e32 v184, v184, v185
	v_add_f32_e32 v225, v182, v184
	v_mul_f32_e32 v182, v103, v103
	v_mul_f32_e32 v183, v105, v105
	v_mul_f32_e32 v184, v99, v99
	v_mul_f32_e32 v185, v101, v101
	v_fmac_f32_e32 v182, v102, v102
	v_fmac_f32_e32 v183, v104, v104
	v_fmac_f32_e32 v184, v98, v98
	v_fmac_f32_e32 v185, v100, v100
	v_add_f32_e32 v182, v182, v183
	v_add_f32_e32 v184, v184, v185
	v_add_f32_e32 v182, v182, v184
	v_add_f32_e32 v225, v225, v182
	v_add_u32_e32 v224, 0x8000, v250
	global_store_dwordx4 v224, v[174:177], s[64:65]
	global_store_dwordx4 v224, v[178:181], s[64:65] offset:256
	v_mov_b32_e32 v226, v225
	s_nop 1
	v_permlane16_swap_b32_e32 v225, v226
	v_add_f32_e32 v225, v225, v226
	v_mov_b32_e32 v226, v225
	s_nop 1
	v_permlane32_swap_b32_e32 v225, v226
	v_add_f32_e32 v225, v225, v226
	s_mov_b64 exec, s[0:1]
	global_atomic_add_f32 v167, v225, s[10:11] offset:64
	s_mov_b64 exec, -1
	v_add_u32_e32 v223, 0x90000, v222
	global_load_dwordx4 v[174:177], v223, s[98:99]
	global_load_dwordx4 v[178:181], v223, s[98:99] offset:16
	global_load_dwordx4 v[182:185], v223, s[98:99] offset:512
	global_load_dwordx4 v[186:189], v223, s[98:99] offset:528
	s_waitcnt vmcnt(12)
; __device__ __forceinline__ unsigned pk(float lo, float hi) { return pg8::cvt_pk_bf16(lo, hi); }
; __device__ __forceinline__ float dot4(f32x4 v) { return (v[0] * v[0] + v[1] * v[1]) + (v[2] * v[2] + v[3] * v[3]); }
;     __device__ __forceinline__ void operator()(const pg8::f32x4 (&acc)[2][2][4][2], const pg8::Unit& u, int wr, int wc, int fr, int fq) const {
;     ...
;             for (int m = 0; m < 4; ++m) {
;                 const int row = row0 + ai * 128 + m * 16;
;                 const float* xi = (row < MP) ? xin_p + (size_t)row * DM : xin_s + (size_t)(row - MP) * DM;
;                 float sq = 0.f;
; #pragma unroll
;                 for (int bj = 0; bj < 2; ++bj) { const int col = u.pn * 256 + bj * 128 + wc * 32 + 8 * fq;
;                     const f32x4 a0 = *(const f32x4*)(xi + col) + acc[ai][bj][m][0], a1 = *(const f32x4*)(xi + col + 4) + acc[ai][bj][m][1];
;                     *(f32x4*)(xout + (size_t)row * DM + col) = a0; *(f32x4*)(xout + (size_t)row * DM + col + 4) = a1;
;                     u32x4 w; w.x = pk(a0[0], a0[1]); w.y = pk(a0[2], a0[3]); w.z = pk(a1[0], a1[1]); w.w = pk(a1[2], a1[3]);
;                     *(u32x4*)(xb + (size_t)row * DM + col) = w;
;                     sq += dot4(a0) + dot4(a1); }
;                 sq += __shfl_xor(sq, 16); sq += __shfl_xor(sq, 32);
;                 if (fq == 0) atomicAdd(ssout + row, sq);
	v_pk_add_f32 v[94:95], v[94:95], v[190:191]
	v_pk_add_f32 v[96:97], v[96:97], v[192:193]
	v_pk_add_f32 v[90:91], v[90:91], v[194:195]
	v_pk_add_f32 v[92:93], v[92:93], v[196:197]
	v_pk_add_f32 v[86:87], v[86:87], v[198:199]
	v_pk_add_f32 v[88:89], v[88:89], v[200:201]
	v_pk_add_f32 v[82:83], v[82:83], v[202:203]
	v_pk_add_f32 v[84:85], v[84:85], v[204:205]
	v_add_u32_e32 v224, 0x20000, v251
	global_store_dwordx4 v224, v[94:97], s[16:17]
	global_store_dwordx4 v224, v[90:93], s[16:17] offset:16
	global_store_dwordx4 v224, v[86:89], s[16:17] offset:512
	global_store_dwordx4 v224, v[82:85], s[16:17] offset:528
	v_cvt_pk_bf16_f32 v190, v94, v95
	v_cvt_pk_bf16_f32 v191, v96, v97
	v_cvt_pk_bf16_f32 v192, v90, v91
	v_cvt_pk_bf16_f32 v193, v92, v93
	v_cvt_pk_bf16_f32 v194, v86, v87
	v_cvt_pk_bf16_f32 v195, v88, v89
	v_cvt_pk_bf16_f32 v196, v82, v83
	v_cvt_pk_bf16_f32 v197, v84, v85
	v_mul_f32_e32 v198, v95, v95
	v_mul_f32_e32 v199, v97, v97
	v_mul_f32_e32 v200, v91, v91
	v_mul_f32_e32 v201, v93, v93
	v_fmac_f32_e32 v198, v94, v94
	v_fmac_f32_e32 v199, v96, v96
	v_fmac_f32_e32 v200, v90, v90
	v_fmac_f32_e32 v201, v92, v92
	v_add_f32_e32 v198, v198, v199
	v_add_f32_e32 v200, v200, v201
	v_add_f32_e32 v225, v198, v200
	v_mul_f32_e32 v198, v87, v87
	v_mul_f32_e32 v199, v89, v89
	v_mul_f32_e32 v200, v83, v83
	v_mul_f32_e32 v201, v85, v85
	v_fmac_f32_e32 v198, v86, v86
	v_fmac_f32_e32 v199, v88, v88
	v_fmac_f32_e32 v200, v82, v82
	v_fmac_f32_e32 v201, v84, v84
	v_add_f32_e32 v198, v198, v199
	v_add_f32_e32 v200, v200, v201
	v_add_f32_e32 v198, v198, v200
	v_add_f32_e32 v225, v225, v198
	v_add_u32_e32 v224, 0x10000, v250
	global_store_dwordx4 v224, v[190:193], s[64:65]
	global_store_dwordx4 v224, v[194:197], s[64:65] offset:256
	v_mov_b32_e32 v226, v225
	s_nop 1
	v_permlane16_swap_b32_e32 v225, v226
	v_add_f32_e32 v225, v225, v226
	v_mov_b32_e32 v226, v225
	s_nop 1
	v_permlane32_swap_b32_e32 v225, v226
	v_add_f32_e32 v225, v225, v226
	s_mov_b64 exec, s[0:1]
	global_atomic_add_f32 v167, v225, s[10:11] offset:128
	s_mov_b64 exec, -1
	v_add_u32_e32 v223, 0xa0000, v222
	global_load_dwordx4 v[190:193], v223, s[98:99]
	global_load_dwordx4 v[194:197], v223, s[98:99] offset:16
	global_load_dwordx4 v[198:201], v223, s[98:99] offset:512
	global_load_dwordx4 v[202:205], v223, s[98:99] offset:528
	s_waitcnt vmcnt(12)
	v_pk_add_f32 v[78:79], v[78:79], v[206:207]
	v_pk_add_f32 v[80:81], v[80:81], v[208:209]
	v_pk_add_f32 v[74:75], v[74:75], v[210:211]
	v_pk_add_f32 v[76:77], v[76:77], v[212:213]
	v_pk_add_f32 v[70:71], v[70:71], v[214:215]
	v_pk_add_f32 v[72:73], v[72:73], v[216:217]
	v_pk_add_f32 v[66:67], v[66:67], v[218:219]
	v_pk_add_f32 v[68:69], v[68:69], v[220:221]
	v_add_u32_e32 v224, 0x30000, v251
	global_store_dwordx4 v224, v[78:81], s[16:17]
	global_store_dwordx4 v224, v[74:77], s[16:17] offset:16
	global_store_dwordx4 v224, v[70:73], s[16:17] offset:512
	global_store_dwordx4 v224, v[66:69], s[16:17] offset:528
	v_cvt_pk_bf16_f32 v206, v78, v79
	v_cvt_pk_bf16_f32 v207, v80, v81
	v_cvt_pk_bf16_f32 v208, v74, v75
	v_cvt_pk_bf16_f32 v209, v76, v77
	v_cvt_pk_bf16_f32 v210, v70, v71
	v_cvt_pk_bf16_f32 v211, v72, v73
	v_cvt_pk_bf16_f32 v212, v66, v67
	v_cvt_pk_bf16_f32 v213, v68, v69
	v_mul_f32_e32 v214, v79, v79
	v_mul_f32_e32 v215, v81, v81
	v_mul_f32_e32 v216, v75, v75
	v_mul_f32_e32 v217, v77, v77
	v_fmac_f32_e32 v214, v78, v78
	v_fmac_f32_e32 v215, v80, v80
	v_fmac_f32_e32 v216, v74, v74
	v_fmac_f32_e32 v217, v76, v76
	v_add_f32_e32 v214, v214, v215
	v_add_f32_e32 v216, v216, v217
	v_add_f32_e32 v225, v214, v216
	v_mul_f32_e32 v214, v71, v71
	v_mul_f32_e32 v215, v73, v73
	v_mul_f32_e32 v216, v67, v67
	v_mul_f32_e32 v217, v69, v69
	v_fmac_f32_e32 v214, v70, v70
	v_fmac_f32_e32 v215, v72, v72
	v_fmac_f32_e32 v216, v66, v66
	v_fmac_f32_e32 v217, v68, v68
	v_add_f32_e32 v214, v214, v215
	v_add_f32_e32 v216, v216, v217
	v_add_f32_e32 v214, v214, v216
	v_add_f32_e32 v225, v225, v214
	v_add_u32_e32 v224, 0x18000, v250
	global_store_dwordx4 v224, v[206:209], s[64:65]
	global_store_dwordx4 v224, v[210:213], s[64:65] offset:256
	v_mov_b32_e32 v226, v225
	s_nop 1
	v_permlane16_swap_b32_e32 v225, v226
	v_add_f32_e32 v225, v225, v226
	v_mov_b32_e32 v226, v225
	s_nop 1
	v_permlane32_swap_b32_e32 v225, v226
	v_add_f32_e32 v225, v225, v226
	s_mov_b64 exec, s[0:1]
	global_atomic_add_f32 v167, v225, s[10:11] offset:192
	s_mov_b64 exec, -1
	v_add_u32_e32 v223, 0xb0000, v222
	global_load_dwordx4 v[206:209], v223, s[98:99]
	global_load_dwordx4 v[210:213], v223, s[98:99] offset:16
	global_load_dwordx4 v[214:217], v223, s[98:99] offset:512
	global_load_dwordx4 v[218:221], v223, s[98:99] offset:528
	s_waitcnt vmcnt(12)
; __device__ __forceinline__ unsigned pk(float lo, float hi) { return pg8::cvt_pk_bf16(lo, hi); }
; __device__ __forceinline__ float dot4(f32x4 v) { return (v[0] * v[0] + v[1] * v[1]) + (v[2] * v[2] + v[3] * v[3]); }
;     __device__ __forceinline__ void operator()(const pg8::f32x4 (&acc)[2][2][4][2], const pg8::Unit& u, int wr, int wc, int fr, int fq) const {
;     ...
;             for (int m = 0; m < 4; ++m) {
;                 const int row = row0 + ai * 128 + m * 16;
;                 const float* xi = (row < MP) ? xin_p + (size_t)row * DM : xin_s + (size_t)(row - MP) * DM;
;                 float sq = 0.f;
; #pragma unroll
;                 for (int bj = 0; bj < 2; ++bj) { const int col = u.pn * 256 + bj * 128 + wc * 32 + 8 * fq;
;                     const f32x4 a0 = *(const f32x4*)(xi + col) + acc[ai][bj][m][0], a1 = *(const f32x4*)(xi + col + 4) + acc[ai][bj][m][1];
;                     *(f32x4*)(xout + (size_t)row * DM + col) = a0; *(f32x4*)(xout + (size_t)row * DM + col + 4) = a1;
;                     u32x4 w; w.x = pk(a0[0], a0[1]); w.y = pk(a0[2], a0[3]); w.z = pk(a1[0], a1[1]); w.w = pk(a1[2], a1[3]);
;                     *(u32x4*)(xb + (size_t)row * DM + col) = w;
;                     sq += dot4(a0) + dot4(a1); }
;                 sq += __shfl_xor(sq, 16); sq += __shfl_xor(sq, 32);
;                 if (fq == 0) atomicAdd(ssout + row, sq);
	v_pk_add_f32 v[62:63], v[62:63], v[146:147]
	v_pk_add_f32 v[64:65], v[64:65], v[148:149]
	v_pk_add_f32 v[58:59], v[58:59], v[150:151]
	v_pk_add_f32 v[60:61], v[60:61], v[152:153]
	v_pk_add_f32 v[54:55], v[54:55], v[162:163]
	v_pk_add_f32 v[56:57], v[56:57], v[164:165]
	v_pk_add_f32 v[50:51], v[50:51], v[170:171]
	v_pk_add_f32 v[52:53], v[52:53], v[172:173]
	v_add_u32_e32 v224, 0x80000, v251
	global_store_dwordx4 v224, v[62:65], s[16:17]
	global_store_dwordx4 v224, v[58:61], s[16:17] offset:16
	global_store_dwordx4 v224, v[54:57], s[16:17] offset:512
	global_store_dwordx4 v224, v[50:53], s[16:17] offset:528
	v_cvt_pk_bf16_f32 v146, v62, v63
	v_cvt_pk_bf16_f32 v147, v64, v65
	v_cvt_pk_bf16_f32 v148, v58, v59
	v_cvt_pk_bf16_f32 v149, v60, v61
	v_cvt_pk_bf16_f32 v150, v54, v55
	v_cvt_pk_bf16_f32 v151, v56, v57
	v_cvt_pk_bf16_f32 v152, v50, v51
	v_cvt_pk_bf16_f32 v153, v52, v53
	v_mul_f32_e32 v162, v63, v63
	v_mul_f32_e32 v163, v65, v65
	v_mul_f32_e32 v164, v59, v59
	v_mul_f32_e32 v165, v61, v61
	v_fmac_f32_e32 v162, v62, v62
	v_fmac_f32_e32 v163, v64, v64
	v_fmac_f32_e32 v164, v58, v58
	v_fmac_f32_e32 v165, v60, v60
	v_add_f32_e32 v162, v162, v163
	v_add_f32_e32 v164, v164, v165
	v_add_f32_e32 v225, v162, v164
	v_mul_f32_e32 v162, v55, v55
	v_mul_f32_e32 v163, v57, v57
	v_mul_f32_e32 v164, v51, v51
	v_mul_f32_e32 v165, v53, v53
	v_fmac_f32_e32 v162, v54, v54
	v_fmac_f32_e32 v163, v56, v56
	v_fmac_f32_e32 v164, v50, v50
	v_fmac_f32_e32 v165, v52, v52
	v_add_f32_e32 v162, v162, v163
	v_add_f32_e32 v164, v164, v165
	v_add_f32_e32 v162, v162, v164
	v_add_f32_e32 v225, v225, v162
	v_add_u32_e32 v224, 0x40000, v250
	global_store_dwordx4 v224, v[146:149], s[64:65]
	global_store_dwordx4 v224, v[150:153], s[64:65] offset:256
	v_mov_b32_e32 v226, v225
	s_nop 1
	v_permlane16_swap_b32_e32 v225, v226
	v_add_f32_e32 v225, v225, v226
	v_mov_b32_e32 v226, v225
	s_nop 1
	v_permlane32_swap_b32_e32 v225, v226
	v_add_f32_e32 v225, v225, v226
	s_mov_b64 exec, s[0:1]
	global_atomic_add_f32 v167, v225, s[10:11] offset:512
	s_mov_b64 exec, -1
	s_waitcnt vmcnt(8)
	v_pk_add_f32 v[46:47], v[46:47], v[174:175]
	v_pk_add_f32 v[48:49], v[48:49], v[176:177]
	v_pk_add_f32 v[42:43], v[42:43], v[178:179]
	v_pk_add_f32 v[44:45], v[44:45], v[180:181]
	v_pk_add_f32 v[38:39], v[38:39], v[182:183]
	v_pk_add_f32 v[40:41], v[40:41], v[184:185]
	v_pk_add_f32 v[34:35], v[34:35], v[186:187]
	v_pk_add_f32 v[36:37], v[36:37], v[188:189]
	v_add_u32_e32 v224, 0x90000, v251
	global_store_dwordx4 v224, v[46:49], s[16:17]
	global_store_dwordx4 v224, v[42:45], s[16:17] offset:16
	global_store_dwordx4 v224, v[38:41], s[16:17] offset:512
	global_store_dwordx4 v224, v[34:37], s[16:17] offset:528
	v_cvt_pk_bf16_f32 v174, v46, v47
	v_cvt_pk_bf16_f32 v175, v48, v49
	v_cvt_pk_bf16_f32 v176, v42, v43
	v_cvt_pk_bf16_f32 v177, v44, v45
	v_cvt_pk_bf16_f32 v178, v38, v39
	v_cvt_pk_bf16_f32 v179, v40, v41
	v_cvt_pk_bf16_f32 v180, v34, v35
	v_cvt_pk_bf16_f32 v181, v36, v37
	v_mul_f32_e32 v182, v47, v47
	v_mul_f32_e32 v183, v49, v49
	v_mul_f32_e32 v184, v43, v43
	v_mul_f32_e32 v185, v45, v45
	v_fmac_f32_e32 v182, v46, v46
	v_fmac_f32_e32 v183, v48, v48
	v_fmac_f32_e32 v184, v42, v42
	v_fmac_f32_e32 v185, v44, v44
	v_add_f32_e32 v182, v182, v183
	v_add_f32_e32 v184, v184, v185
	v_add_f32_e32 v225, v182, v184
	v_mul_f32_e32 v182, v39, v39
	v_mul_f32_e32 v183, v41, v41
	v_mul_f32_e32 v184, v35, v35
	v_mul_f32_e32 v185, v37, v37
	v_fmac_f32_e32 v182, v38, v38
	v_fmac_f32_e32 v183, v40, v40
	v_fmac_f32_e32 v184, v34, v34
	v_fmac_f32_e32 v185, v36, v36
	v_add_f32_e32 v182, v182, v183
	v_add_f32_e32 v184, v184, v185
	v_add_f32_e32 v182, v182, v184
	v_add_f32_e32 v225, v225, v182
	v_add_u32_e32 v224, 0x48000, v250
	global_store_dwordx4 v224, v[174:177], s[64:65]
	global_store_dwordx4 v224, v[178:181], s[64:65] offset:256
	v_mov_b32_e32 v226, v225
	s_nop 1
	v_permlane16_swap_b32_e32 v225, v226
	v_add_f32_e32 v225, v225, v226
	v_mov_b32_e32 v226, v225
	s_nop 1
	v_permlane32_swap_b32_e32 v225, v226
	v_add_f32_e32 v225, v225, v226
	s_mov_b64 exec, s[0:1]
	global_atomic_add_f32 v167, v225, s[10:11] offset:576
	s_mov_b64 exec, -1
	s_waitcnt vmcnt(4)
; #define PG8_BAR __builtin_amdgcn_s_barrier()
; __device__ __forceinline__ unsigned pk(float lo, float hi) { return pg8::cvt_pk_bf16(lo, hi); }
; __device__ __forceinline__ float dot4(f32x4 v) { return (v[0] * v[0] + v[1] * v[1]) + (v[2] * v[2] + v[3] * v[3]); }
; template <class Epi, class Sched, bool ALIGN_EPI = false, bool SP2 = false>
; __device__ __forceinline__ void gemm_phase(PG8_LAS unsigned char* lds, const Gemm g, const Sched& S, const Epi& E) {
;     ...
;         if (!has_next) break;
; #pragma unroll
;         for (int a = 0; a < 2; ++a)
; #pragma unroll
;             for (int b = 0; b < 2; ++b)
; #pragma unroll
;                 for (int m = 0; m < 4; ++m)
; #pragma unroll
;                     for (int n = 0; n < 2; ++n) acc[a][b][m][n] = (f32x4){0.f, 0.f, 0.f, 0.f};
;         cur = nxt; cA = nA; cB = nB; ++ui;
;         if constexpr (ALIGN_EPI) { if (wr == 1) PG8_BAR; }
;     }
;     __device__ __forceinline__ void operator()(const pg8::f32x4 (&acc)[2][2][4][2], const pg8::Unit& u, int wr, int wc, int fr, int fq) const {
;     ...
;             for (int m = 0; m < 4; ++m) {
;                 const int row = row0 + ai * 128 + m * 16;
;                 const float* xi = (row < MP) ? xin_p + (size_t)row * DM : xin_s + (size_t)(row - MP) * DM;
;                 float sq = 0.f;
; #pragma unroll
;                 for (int bj = 0; bj < 2; ++bj) { const int col = u.pn * 256 + bj * 128 + wc * 32 + 8 * fq;
;                     const f32x4 a0 = *(const f32x4*)(xi + col) + acc[ai][bj][m][0], a1 = *(const f32x4*)(xi + col + 4) + acc[ai][bj][m][1];
;                     *(f32x4*)(xout + (size_t)row * DM + col) = a0; *(f32x4*)(xout + (size_t)row * DM + col + 4) = a1;
;                     u32x4 w; w.x = pk(a0[0], a0[1]); w.y = pk(a0[2], a0[3]); w.z = pk(a1[0], a1[1]); w.w = pk(a1[2], a1[3]);
;                     *(u32x4*)(xb + (size_t)row * DM + col) = w;
;                     sq += dot4(a0) + dot4(a1); }
;                 sq += __shfl_xor(sq, 16); sq += __shfl_xor(sq, 32);
;                 if (fq == 0) atomicAdd(ssout + row, sq);
;             }
;     }
	v_pk_add_f32 v[30:31], v[30:31], v[190:191]
	v_pk_add_f32 v[32:33], v[32:33], v[192:193]
	v_pk_add_f32 v[26:27], v[26:27], v[194:195]
	v_pk_add_f32 v[28:29], v[28:29], v[196:197]
	v_pk_add_f32 v[22:23], v[22:23], v[198:199]
	v_pk_add_f32 v[24:25], v[24:25], v[200:201]
	v_pk_add_f32 v[18:19], v[18:19], v[202:203]
	v_pk_add_f32 v[20:21], v[20:21], v[204:205]
	v_add_u32_e32 v224, 0xa0000, v251
	global_store_dwordx4 v224, v[30:33], s[16:17]
	global_store_dwordx4 v224, v[26:29], s[16:17] offset:16
	global_store_dwordx4 v224, v[22:25], s[16:17] offset:512
	global_store_dwordx4 v224, v[18:21], s[16:17] offset:528
	v_cvt_pk_bf16_f32 v190, v30, v31
	v_cvt_pk_bf16_f32 v191, v32, v33
	v_cvt_pk_bf16_f32 v192, v26, v27
	v_cvt_pk_bf16_f32 v193, v28, v29
	v_cvt_pk_bf16_f32 v194, v22, v23
	v_cvt_pk_bf16_f32 v195, v24, v25
	v_cvt_pk_bf16_f32 v196, v18, v19
	v_cvt_pk_bf16_f32 v197, v20, v21
	v_mul_f32_e32 v198, v31, v31
	v_mul_f32_e32 v199, v33, v33
	v_mul_f32_e32 v200, v27, v27
	v_mul_f32_e32 v201, v29, v29
	v_fmac_f32_e32 v198, v30, v30
	v_fmac_f32_e32 v199, v32, v32
	v_fmac_f32_e32 v200, v26, v26
	v_fmac_f32_e32 v201, v28, v28
	v_add_f32_e32 v198, v198, v199
	v_add_f32_e32 v200, v200, v201
	v_add_f32_e32 v225, v198, v200
	v_mul_f32_e32 v198, v23, v23
	v_mul_f32_e32 v199, v25, v25
	v_mul_f32_e32 v200, v19, v19
	v_mul_f32_e32 v201, v21, v21
	v_fmac_f32_e32 v198, v22, v22
	v_fmac_f32_e32 v199, v24, v24
	v_fmac_f32_e32 v200, v18, v18
	v_fmac_f32_e32 v201, v20, v20
	v_add_f32_e32 v198, v198, v199
	v_add_f32_e32 v200, v200, v201
	v_add_f32_e32 v198, v198, v200
	v_add_f32_e32 v225, v225, v198
	v_add_u32_e32 v224, 0x50000, v250
	global_store_dwordx4 v224, v[190:193], s[64:65]
	global_store_dwordx4 v224, v[194:197], s[64:65] offset:256
	v_mov_b32_e32 v226, v225
	s_nop 1
	v_permlane16_swap_b32_e32 v225, v226
	v_add_f32_e32 v225, v225, v226
	v_mov_b32_e32 v226, v225
	s_nop 1
	v_permlane32_swap_b32_e32 v225, v226
	v_add_f32_e32 v225, v225, v226
	s_mov_b64 exec, s[0:1]
	global_atomic_add_f32 v167, v225, s[10:11] offset:640
	s_mov_b64 exec, -1
	s_waitcnt vmcnt(0)
	v_pk_add_f32 v[14:15], v[14:15], v[206:207]
	v_pk_add_f32 v[16:17], v[16:17], v[208:209]
	v_pk_add_f32 v[10:11], v[10:11], v[210:211]
	v_pk_add_f32 v[12:13], v[12:13], v[212:213]
	v_pk_add_f32 v[6:7], v[6:7], v[214:215]
	v_pk_add_f32 v[8:9], v[8:9], v[216:217]
	v_pk_add_f32 v[2:3], v[2:3], v[218:219]
	v_pk_add_f32 v[4:5], v[4:5], v[220:221]
	v_add_u32_e32 v224, 0xb0000, v251
	global_store_dwordx4 v224, v[14:17], s[16:17]
	global_store_dwordx4 v224, v[10:13], s[16:17] offset:16
	global_store_dwordx4 v224, v[6:9], s[16:17] offset:512
	global_store_dwordx4 v224, v[2:5], s[16:17] offset:528
	v_cvt_pk_bf16_f32 v206, v14, v15
	v_cvt_pk_bf16_f32 v207, v16, v17
	v_cvt_pk_bf16_f32 v208, v10, v11
	v_cvt_pk_bf16_f32 v209, v12, v13
	v_cvt_pk_bf16_f32 v210, v6, v7
	v_cvt_pk_bf16_f32 v211, v8, v9
	v_cvt_pk_bf16_f32 v212, v2, v3
	v_cvt_pk_bf16_f32 v213, v4, v5
	v_mul_f32_e32 v214, v15, v15
	v_mul_f32_e32 v215, v17, v17
	v_mul_f32_e32 v216, v11, v11
	v_mul_f32_e32 v217, v13, v13
	v_fmac_f32_e32 v214, v14, v14
	v_fmac_f32_e32 v215, v16, v16
	v_fmac_f32_e32 v216, v10, v10
	v_fmac_f32_e32 v217, v12, v12
	v_add_f32_e32 v214, v214, v215
	v_add_f32_e32 v216, v216, v217
	v_add_f32_e32 v225, v214, v216
	v_mul_f32_e32 v214, v7, v7
	v_mul_f32_e32 v215, v9, v9
	v_mul_f32_e32 v216, v3, v3
	v_mul_f32_e32 v217, v5, v5
	v_fmac_f32_e32 v214, v6, v6
	v_fmac_f32_e32 v215, v8, v8
	v_fmac_f32_e32 v216, v2, v2
	v_fmac_f32_e32 v217, v4, v4
	v_add_f32_e32 v214, v214, v215
	v_add_f32_e32 v216, v216, v217
	v_add_f32_e32 v214, v214, v216
	v_add_f32_e32 v225, v225, v214
	v_add_u32_e32 v224, 0x58000, v250
	global_store_dwordx4 v224, v[206:209], s[64:65]
	global_store_dwordx4 v224, v[210:213], s[64:65] offset:256
	v_mov_b32_e32 v226, v225
	s_nop 1
	v_permlane16_swap_b32_e32 v225, v226
	v_add_f32_e32 v225, v225, v226
	v_mov_b32_e32 v226, v225
	s_nop 1
	v_permlane32_swap_b32_e32 v225, v226
	v_add_f32_e32 v225, v225, v226
	s_mov_b64 exec, s[0:1]
	global_atomic_add_f32 v167, v225, s[10:11] offset:704
	s_mov_b64 exec, -1
	s_andn2_b64 vcc, exec, s[4:5]
	s_mov_b64 s[4:5], -1
	s_cbranch_vccnz .LBB0_779
	s_andn2_b64 vcc, exec, s[8:9]
	s_cbranch_vccnz .LBB0_778
	s_barrier
	s_branch .LBB0_778

; __device__ __forceinline__ unsigned pk(float lo, float hi) { return pg8::cvt_pk_bf16(lo, hi); }
; __device__ __forceinline__ float dot4(f32x4 v) { return (v[0] * v[0] + v[1] * v[1]) + (v[2] * v[2] + v[3] * v[3]); }
;     __device__ __forceinline__ void operator()(const pg8::f32x4 (&acc)[2][2][4][2], const pg8::Unit& u, int wr, int wc, int fr, int fq) const {
;         const int row0 = u.pm * 256 + wr * 64 + fr;
; #pragma unroll
;         for (int ai = 0; ai < 2; ++ai)
; #pragma unroll
;             for (int m = 0; m < 4; ++m) {
;                 const int row = row0 + ai * 128 + m * 16;
;                 const float* xi = (row < MP) ? xin_p + (size_t)row * DM : xin_s + (size_t)(row - MP) * DM;
;                 float sq = 0.f;
; #pragma unroll
;                 for (int bj = 0; bj < 2; ++bj) { const int col = u.pn * 256 + bj * 128 + wc * 32 + 8 * fq;
;                     const f32x4 a0 = *(const f32x4*)(xi + col) + acc[ai][bj][m][0], a1 = *(const f32x4*)(xi + col + 4) + acc[ai][bj][m][1];
;                     *(f32x4*)(xout + (size_t)row * DM + col) = a0; *(f32x4*)(xout + (size_t)row * DM + col + 4) = a1;
;                     u32x4 w; w.x = pk(a0[0], a0[1]); w.y = pk(a0[2], a0[3]); w.z = pk(a1[0], a1[1]); w.w = pk(a1[2], a1[3]);
;                     *(u32x4*)(xb + (size_t)row * DM + col) = w;
;                     sq += dot4(a0) + dot4(a1); }
;                 sq += __shfl_xor(sq, 16); sq += __shfl_xor(sq, 32);
;                 if (fq == 0) atomicAdd(ssout + row, sq);
.LBB0_1063:
	s_cmp_lt_u32 s72, 64
	s_cselect_b32 s98, s16, s8
	s_cselect_b32 s99, s17, s9
	s_cselect_b32 s100, 0, 0x4000
	v_lshl_add_u32 v138, s72, 8, v163
	v_lshl_or_b32 v185, s71, 8, v165
	v_lshlrev_b32_e32 v251, 2, v138
	v_lshlrev_b32_e32 v250, 1, v185
	v_lshl_add_u32 v242, v138, 11, v250
	v_lshlrev_b32_e32 v250, 2, v185
	v_lshl_add_u32 v243, v138, 12, v250
	v_subrev_u32_e32 v138, s100, v138
	v_lshl_add_u32 v244, v138, 12, v250
	global_load_dwordx4 v[148:151], v244, s[98:99]
	global_load_dwordx4 v[152:155], v244, s[98:99] offset:16
	global_load_dwordx4 v[186:189], v244, s[98:99] offset:512
	global_load_dwordx4 v[190:193], v244, s[98:99] offset:528
	v_add_u32_e32 v245, 0x10000, v244
	global_load_dwordx4 v[194:197], v245, s[98:99]
	global_load_dwordx4 v[198:201], v245, s[98:99] offset:16
	global_load_dwordx4 v[202:205], v245, s[98:99] offset:512
	global_load_dwordx4 v[206:209], v245, s[98:99] offset:528
	v_add_u32_e32 v245, 0x20000, v244
	global_load_dwordx4 v[210:213], v245, s[98:99]
	global_load_dwordx4 v[214:217], v245, s[98:99] offset:16
	global_load_dwordx4 v[218:221], v245, s[98:99] offset:512
	global_load_dwordx4 v[222:225], v245, s[98:99] offset:528
	v_add_u32_e32 v245, 0x30000, v244
	global_load_dwordx4 v[226:229], v245, s[98:99]
	global_load_dwordx4 v[230:233], v245, s[98:99] offset:16
	global_load_dwordx4 v[234:237], v245, s[98:99] offset:512
	global_load_dwordx4 v[238:241], v245, s[98:99] offset:528
	s_waitcnt vmcnt(12)
	v_pk_add_f32 v[126:127], v[126:127], v[148:149]
	v_pk_add_f32 v[128:129], v[128:129], v[150:151]
	v_pk_add_f32 v[122:123], v[122:123], v[152:153]
	v_pk_add_f32 v[124:125], v[124:125], v[154:155]
	v_pk_add_f32 v[118:119], v[118:119], v[186:187]
	v_pk_add_f32 v[120:121], v[120:121], v[188:189]
	v_pk_add_f32 v[114:115], v[114:115], v[190:191]
	v_pk_add_f32 v[116:117], v[116:117], v[192:193]
	global_store_dwordx4 v243, v[126:129], s[16:17]
	global_store_dwordx4 v243, v[122:125], s[16:17] offset:16
	global_store_dwordx4 v243, v[118:121], s[16:17] offset:512
	global_store_dwordx4 v243, v[114:117], s[16:17] offset:528
	v_cvt_pk_bf16_f32 v148, v126, v127
	v_cvt_pk_bf16_f32 v149, v128, v129
	v_cvt_pk_bf16_f32 v150, v122, v123
	v_cvt_pk_bf16_f32 v151, v124, v125
	v_cvt_pk_bf16_f32 v152, v118, v119
	v_cvt_pk_bf16_f32 v153, v120, v121
	v_cvt_pk_bf16_f32 v154, v114, v115
	v_cvt_pk_bf16_f32 v155, v116, v117
	v_mul_f32_e32 v186, v127, v127
	v_mul_f32_e32 v187, v129, v129
	v_mul_f32_e32 v188, v123, v123
	v_mul_f32_e32 v189, v125, v125
	v_fmac_f32_e32 v186, v126, v126
	v_fmac_f32_e32 v187, v128, v128
	v_fmac_f32_e32 v188, v122, v122
	v_fmac_f32_e32 v189, v124, v124
	v_add_f32_e32 v186, v186, v187
	v_add_f32_e32 v188, v188, v189
	v_add_f32_e32 v247, v186, v188
	v_mul_f32_e32 v186, v119, v119
	v_mul_f32_e32 v187, v121, v121
	v_mul_f32_e32 v188, v115, v115
	v_mul_f32_e32 v189, v117, v117
	v_fmac_f32_e32 v186, v118, v118
	v_fmac_f32_e32 v187, v120, v120
	v_fmac_f32_e32 v188, v114, v114
	v_fmac_f32_e32 v189, v116, v116
	v_add_f32_e32 v186, v186, v187
	v_add_f32_e32 v188, v188, v189
	v_add_f32_e32 v186, v186, v188
	v_add_f32_e32 v247, v247, v186
	global_store_dwordx4 v242, v[148:151], s[64:65]
	global_store_dwordx4 v242, v[152:155], s[64:65] offset:256
	v_mov_b32_e32 v248, v247
	s_nop 1
	v_permlane16_swap_b32_e32 v247, v248
	v_add_f32_e32 v247, v247, v248
	v_mov_b32_e32 v248, v247
	s_nop 1
	v_permlane32_swap_b32_e32 v247, v248
	v_add_f32_e32 v247, v247, v248
	s_mov_b64 exec, s[0:1]
	global_atomic_add_f32 v251, v247, s[10:11]
	s_mov_b64 exec, -1
	v_add_u32_e32 v245, 0x80000, v244
	global_load_dwordx4 v[148:151], v245, s[98:99]
	global_load_dwordx4 v[152:155], v245, s[98:99] offset:16
	global_load_dwordx4 v[186:189], v245, s[98:99] offset:512
	global_load_dwordx4 v[190:193], v245, s[98:99] offset:528
	s_waitcnt vmcnt(12)
	v_pk_add_f32 v[110:111], v[110:111], v[194:195]
	v_pk_add_f32 v[112:113], v[112:113], v[196:197]
	v_pk_add_f32 v[106:107], v[106:107], v[198:199]
	v_pk_add_f32 v[108:109], v[108:109], v[200:201]
	v_pk_add_f32 v[102:103], v[102:103], v[202:203]
	v_pk_add_f32 v[104:105], v[104:105], v[204:205]
	v_pk_add_f32 v[98:99], v[98:99], v[206:207]
	v_pk_add_f32 v[100:101], v[100:101], v[208:209]
	v_add_u32_e32 v246, 0x10000, v243
	global_store_dwordx4 v246, v[110:113], s[16:17]
	global_store_dwordx4 v246, v[106:109], s[16:17] offset:16
	global_store_dwordx4 v246, v[102:105], s[16:17] offset:512
	global_store_dwordx4 v246, v[98:101], s[16:17] offset:528
	v_cvt_pk_bf16_f32 v194, v110, v111
	v_cvt_pk_bf16_f32 v195, v112, v113
	v_cvt_pk_bf16_f32 v196, v106, v107
	v_cvt_pk_bf16_f32 v197, v108, v109
	v_cvt_pk_bf16_f32 v198, v102, v103
	v_cvt_pk_bf16_f32 v199, v104, v105
	v_cvt_pk_bf16_f32 v200, v98, v99
	v_cvt_pk_bf16_f32 v201, v100, v101
	v_mul_f32_e32 v202, v111, v111
	v_mul_f32_e32 v203, v113, v113
	v_mul_f32_e32 v204, v107, v107
	v_mul_f32_e32 v205, v109, v109
	v_fmac_f32_e32 v202, v110, v110
	v_fmac_f32_e32 v203, v112, v112
	v_fmac_f32_e32 v204, v106, v106
	v_fmac_f32_e32 v205, v108, v108
	v_add_f32_e32 v202, v202, v203
	v_add_f32_e32 v204, v204, v205
	v_add_f32_e32 v247, v202, v204
	v_mul_f32_e32 v202, v103, v103
	v_mul_f32_e32 v203, v105, v105
	v_mul_f32_e32 v204, v99, v99
	v_mul_f32_e32 v205, v101, v101
	v_fmac_f32_e32 v202, v102, v102
	v_fmac_f32_e32 v203, v104, v104
	v_fmac_f32_e32 v204, v98, v98
	v_fmac_f32_e32 v205, v100, v100
	v_add_f32_e32 v202, v202, v203
	v_add_f32_e32 v204, v204, v205
	v_add_f32_e32 v202, v202, v204
	v_add_f32_e32 v247, v247, v202
	v_add_u32_e32 v246, 0x8000, v242
	global_store_dwordx4 v246, v[194:197], s[64:65]
	global_store_dwordx4 v246, v[198:201], s[64:65] offset:256
	v_mov_b32_e32 v248, v247
	s_nop 1
	v_permlane16_swap_b32_e32 v247, v248
	v_add_f32_e32 v247, v247, v248
	v_mov_b32_e32 v248, v247
	s_nop 1
	v_permlane32_swap_b32_e32 v247, v248
	v_add_f32_e32 v247, v247, v248
	s_mov_b64 exec, s[0:1]
	global_atomic_add_f32 v251, v247, s[10:11] offset:64
	s_mov_b64 exec, -1
	v_add_u32_e32 v245, 0x90000, v244
	global_load_dwordx4 v[194:197], v245, s[98:99]
	global_load_dwordx4 v[198:201], v245, s[98:99] offset:16
	global_load_dwordx4 v[202:205], v245, s[98:99] offset:512
	global_load_dwordx4 v[206:209], v245, s[98:99] offset:528
	s_waitcnt vmcnt(12)
; __device__ __forceinline__ unsigned pk(float lo, float hi) { return pg8::cvt_pk_bf16(lo, hi); }
; __device__ __forceinline__ float dot4(f32x4 v) { return (v[0] * v[0] + v[1] * v[1]) + (v[2] * v[2] + v[3] * v[3]); }
;     __device__ __forceinline__ void operator()(const pg8::f32x4 (&acc)[2][2][4][2], const pg8::Unit& u, int wr, int wc, int fr, int fq) const {
;     ...
;             for (int m = 0; m < 4; ++m) {
;                 const int row = row0 + ai * 128 + m * 16;
;                 const float* xi = (row < MP) ? xin_p + (size_t)row * DM : xin_s + (size_t)(row - MP) * DM;
;                 float sq = 0.f;
; #pragma unroll
;                 for (int bj = 0; bj < 2; ++bj) { const int col = u.pn * 256 + bj * 128 + wc * 32 + 8 * fq;
;                     const f32x4 a0 = *(const f32x4*)(xi + col) + acc[ai][bj][m][0], a1 = *(const f32x4*)(xi + col + 4) + acc[ai][bj][m][1];
;                     *(f32x4*)(xout + (size_t)row * DM + col) = a0; *(f32x4*)(xout + (size_t)row * DM + col + 4) = a1;
;                     u32x4 w; w.x = pk(a0[0], a0[1]); w.y = pk(a0[2], a0[3]); w.z = pk(a1[0], a1[1]); w.w = pk(a1[2], a1[3]);
;                     *(u32x4*)(xb + (size_t)row * DM + col) = w;
;                     sq += dot4(a0) + dot4(a1); }
;                 sq += __shfl_xor(sq, 16); sq += __shfl_xor(sq, 32);
;                 if (fq == 0) atomicAdd(ssout + row, sq);
	v_pk_add_f32 v[94:95], v[94:95], v[210:211]
	v_pk_add_f32 v[96:97], v[96:97], v[212:213]
	v_pk_add_f32 v[90:91], v[90:91], v[214:215]
	v_pk_add_f32 v[92:93], v[92:93], v[216:217]
	v_pk_add_f32 v[86:87], v[86:87], v[218:219]
	v_pk_add_f32 v[88:89], v[88:89], v[220:221]
	v_pk_add_f32 v[82:83], v[82:83], v[222:223]
	v_pk_add_f32 v[84:85], v[84:85], v[224:225]
	v_add_u32_e32 v246, 0x20000, v243
	global_store_dwordx4 v246, v[94:97], s[16:17]
	global_store_dwordx4 v246, v[90:93], s[16:17] offset:16
	global_store_dwordx4 v246, v[86:89], s[16:17] offset:512
	global_store_dwordx4 v246, v[82:85], s[16:17] offset:528
	v_cvt_pk_bf16_f32 v210, v94, v95
	v_cvt_pk_bf16_f32 v211, v96, v97
	v_cvt_pk_bf16_f32 v212, v90, v91
	v_cvt_pk_bf16_f32 v213, v92, v93
	v_cvt_pk_bf16_f32 v214, v86, v87
	v_cvt_pk_bf16_f32 v215, v88, v89
	v_cvt_pk_bf16_f32 v216, v82, v83
	v_cvt_pk_bf16_f32 v217, v84, v85
	v_mul_f32_e32 v218, v95, v95
	v_mul_f32_e32 v219, v97, v97
	v_mul_f32_e32 v220, v91, v91
	v_mul_f32_e32 v221, v93, v93
	v_fmac_f32_e32 v218, v94, v94
	v_fmac_f32_e32 v219, v96, v96
	v_fmac_f32_e32 v220, v90, v90
	v_fmac_f32_e32 v221, v92, v92
	v_add_f32_e32 v218, v218, v219
	v_add_f32_e32 v220, v220, v221
	v_add_f32_e32 v247, v218, v220
	v_mul_f32_e32 v218, v87, v87
	v_mul_f32_e32 v219, v89, v89
	v_mul_f32_e32 v220, v83, v83
	v_mul_f32_e32 v221, v85, v85
	v_fmac_f32_e32 v218, v86, v86
	v_fmac_f32_e32 v219, v88, v88
	v_fmac_f32_e32 v220, v82, v82
	v_fmac_f32_e32 v221, v84, v84
	v_add_f32_e32 v218, v218, v219
	v_add_f32_e32 v220, v220, v221
	v_add_f32_e32 v218, v218, v220
	v_add_f32_e32 v247, v247, v218
	v_add_u32_e32 v246, 0x10000, v242
	global_store_dwordx4 v246, v[210:213], s[64:65]
	global_store_dwordx4 v246, v[214:217], s[64:65] offset:256
	v_mov_b32_e32 v248, v247
	s_nop 1
	v_permlane16_swap_b32_e32 v247, v248
	v_add_f32_e32 v247, v247, v248
	v_mov_b32_e32 v248, v247
	s_nop 1
	v_permlane32_swap_b32_e32 v247, v248
	v_add_f32_e32 v247, v247, v248
	s_mov_b64 exec, s[0:1]
	global_atomic_add_f32 v251, v247, s[10:11] offset:128
	s_mov_b64 exec, -1
	v_add_u32_e32 v245, 0xa0000, v244
	global_load_dwordx4 v[210:213], v245, s[98:99]
	global_load_dwordx4 v[214:217], v245, s[98:99] offset:16
	global_load_dwordx4 v[218:221], v245, s[98:99] offset:512
	global_load_dwordx4 v[222:225], v245, s[98:99] offset:528
	s_waitcnt vmcnt(12)
	v_pk_add_f32 v[78:79], v[78:79], v[226:227]
	v_pk_add_f32 v[80:81], v[80:81], v[228:229]
	v_pk_add_f32 v[74:75], v[74:75], v[230:231]
	v_pk_add_f32 v[76:77], v[76:77], v[232:233]
	v_pk_add_f32 v[70:71], v[70:71], v[234:235]
	v_pk_add_f32 v[72:73], v[72:73], v[236:237]
	v_pk_add_f32 v[66:67], v[66:67], v[238:239]
	v_pk_add_f32 v[68:69], v[68:69], v[240:241]
	v_add_u32_e32 v246, 0x30000, v243
	global_store_dwordx4 v246, v[78:81], s[16:17]
	global_store_dwordx4 v246, v[74:77], s[16:17] offset:16
	global_store_dwordx4 v246, v[70:73], s[16:17] offset:512
	global_store_dwordx4 v246, v[66:69], s[16:17] offset:528
	v_cvt_pk_bf16_f32 v226, v78, v79
	v_cvt_pk_bf16_f32 v227, v80, v81
	v_cvt_pk_bf16_f32 v228, v74, v75
	v_cvt_pk_bf16_f32 v229, v76, v77
	v_cvt_pk_bf16_f32 v230, v70, v71
	v_cvt_pk_bf16_f32 v231, v72, v73
	v_cvt_pk_bf16_f32 v232, v66, v67
	v_cvt_pk_bf16_f32 v233, v68, v69
	v_mul_f32_e32 v234, v79, v79
	v_mul_f32_e32 v235, v81, v81
	v_mul_f32_e32 v236, v75, v75
	v_mul_f32_e32 v237, v77, v77
	v_fmac_f32_e32 v234, v78, v78
	v_fmac_f32_e32 v235, v80, v80
	v_fmac_f32_e32 v236, v74, v74
	v_fmac_f32_e32 v237, v76, v76
	v_add_f32_e32 v234, v234, v235
	v_add_f32_e32 v236, v236, v237
	v_add_f32_e32 v247, v234, v236
	v_mul_f32_e32 v234, v71, v71
	v_mul_f32_e32 v235, v73, v73
	v_mul_f32_e32 v236, v67, v67
	v_mul_f32_e32 v237, v69, v69
	v_fmac_f32_e32 v234, v70, v70
	v_fmac_f32_e32 v235, v72, v72
	v_fmac_f32_e32 v236, v66, v66
	v_fmac_f32_e32 v237, v68, v68
	v_add_f32_e32 v234, v234, v235
	v_add_f32_e32 v236, v236, v237
	v_add_f32_e32 v234, v234, v236
	v_add_f32_e32 v247, v247, v234
	v_add_u32_e32 v246, 0x18000, v242
	global_store_dwordx4 v246, v[226:229], s[64:65]
	global_store_dwordx4 v246, v[230:233], s[64:65] offset:256
	v_mov_b32_e32 v248, v247
	s_nop 1
	v_permlane16_swap_b32_e32 v247, v248
	v_add_f32_e32 v247, v247, v248
	v_mov_b32_e32 v248, v247
	s_nop 1
	v_permlane32_swap_b32_e32 v247, v248
	v_add_f32_e32 v247, v247, v248
	s_mov_b64 exec, s[0:1]
	global_atomic_add_f32 v251, v247, s[10:11] offset:192
	s_mov_b64 exec, -1
	v_add_u32_e32 v245, 0xb0000, v244
	global_load_dwordx4 v[226:229], v245, s[98:99]
	global_load_dwordx4 v[230:233], v245, s[98:99] offset:16
	global_load_dwordx4 v[234:237], v245, s[98:99] offset:512
	global_load_dwordx4 v[238:241], v245, s[98:99] offset:528
	s_waitcnt vmcnt(12)
; __device__ __forceinline__ unsigned pk(float lo, float hi) { return pg8::cvt_pk_bf16(lo, hi); }
; __device__ __forceinline__ float dot4(f32x4 v) { return (v[0] * v[0] + v[1] * v[1]) + (v[2] * v[2] + v[3] * v[3]); }
;     __device__ __forceinline__ void operator()(const pg8::f32x4 (&acc)[2][2][4][2], const pg8::Unit& u, int wr, int wc, int fr, int fq) const {
;     ...
;             for (int m = 0; m < 4; ++m) {
;                 const int row = row0 + ai * 128 + m * 16;
;                 const float* xi = (row < MP) ? xin_p + (size_t)row * DM : xin_s + (size_t)(row - MP) * DM;
;                 float sq = 0.f;
; #pragma unroll
;                 for (int bj = 0; bj < 2; ++bj) { const int col = u.pn * 256 + bj * 128 + wc * 32 + 8 * fq;
;                     const f32x4 a0 = *(const f32x4*)(xi + col) + acc[ai][bj][m][0], a1 = *(const f32x4*)(xi + col + 4) + acc[ai][bj][m][1];
;                     *(f32x4*)(xout + (size_t)row * DM + col) = a0; *(f32x4*)(xout + (size_t)row * DM + col + 4) = a1;
;                     u32x4 w; w.x = pk(a0[0], a0[1]); w.y = pk(a0[2], a0[3]); w.z = pk(a1[0], a1[1]); w.w = pk(a1[2], a1[3]);
;                     *(u32x4*)(xb + (size_t)row * DM + col) = w;
;                     sq += dot4(a0) + dot4(a1); }
;                 sq += __shfl_xor(sq, 16); sq += __shfl_xor(sq, 32);
;                 if (fq == 0) atomicAdd(ssout + row, sq);
	v_pk_add_f32 v[62:63], v[62:63], v[148:149]
	v_pk_add_f32 v[64:65], v[64:65], v[150:151]
	v_pk_add_f32 v[58:59], v[58:59], v[152:153]
	v_pk_add_f32 v[60:61], v[60:61], v[154:155]
	v_pk_add_f32 v[54:55], v[54:55], v[186:187]
	v_pk_add_f32 v[56:57], v[56:57], v[188:189]
	v_pk_add_f32 v[50:51], v[50:51], v[190:191]
	v_pk_add_f32 v[52:53], v[52:53], v[192:193]
	v_add_u32_e32 v246, 0x80000, v243
	global_store_dwordx4 v246, v[62:65], s[16:17]
	global_store_dwordx4 v246, v[58:61], s[16:17] offset:16
	global_store_dwordx4 v246, v[54:57], s[16:17] offset:512
	global_store_dwordx4 v246, v[50:53], s[16:17] offset:528
	v_cvt_pk_bf16_f32 v148, v62, v63
	v_cvt_pk_bf16_f32 v149, v64, v65
	v_cvt_pk_bf16_f32 v150, v58, v59
	v_cvt_pk_bf16_f32 v151, v60, v61
	v_cvt_pk_bf16_f32 v152, v54, v55
	v_cvt_pk_bf16_f32 v153, v56, v57
	v_cvt_pk_bf16_f32 v154, v50, v51
	v_cvt_pk_bf16_f32 v155, v52, v53
	v_mul_f32_e32 v186, v63, v63
	v_mul_f32_e32 v187, v65, v65
	v_mul_f32_e32 v188, v59, v59
	v_mul_f32_e32 v189, v61, v61
	v_fmac_f32_e32 v186, v62, v62
	v_fmac_f32_e32 v187, v64, v64
	v_fmac_f32_e32 v188, v58, v58
	v_fmac_f32_e32 v189, v60, v60
	v_add_f32_e32 v186, v186, v187
	v_add_f32_e32 v188, v188, v189
	v_add_f32_e32 v247, v186, v188
	v_mul_f32_e32 v186, v55, v55
	v_mul_f32_e32 v187, v57, v57
	v_mul_f32_e32 v188, v51, v51
	v_mul_f32_e32 v189, v53, v53
	v_fmac_f32_e32 v186, v54, v54
	v_fmac_f32_e32 v187, v56, v56
	v_fmac_f32_e32 v188, v50, v50
	v_fmac_f32_e32 v189, v52, v52
	v_add_f32_e32 v186, v186, v187
	v_add_f32_e32 v188, v188, v189
	v_add_f32_e32 v186, v186, v188
	v_add_f32_e32 v247, v247, v186
	v_add_u32_e32 v246, 0x40000, v242
	global_store_dwordx4 v246, v[148:151], s[64:65]
	global_store_dwordx4 v246, v[152:155], s[64:65] offset:256
	v_mov_b32_e32 v248, v247
	s_nop 1
	v_permlane16_swap_b32_e32 v247, v248
	v_add_f32_e32 v247, v247, v248
	v_mov_b32_e32 v248, v247
	s_nop 1
	v_permlane32_swap_b32_e32 v247, v248
	v_add_f32_e32 v247, v247, v248
	s_mov_b64 exec, s[0:1]
	global_atomic_add_f32 v251, v247, s[10:11] offset:512
	s_mov_b64 exec, -1
	s_waitcnt vmcnt(8)
	v_pk_add_f32 v[46:47], v[46:47], v[194:195]
	v_pk_add_f32 v[48:49], v[48:49], v[196:197]
	v_pk_add_f32 v[42:43], v[42:43], v[198:199]
	v_pk_add_f32 v[44:45], v[44:45], v[200:201]
	v_pk_add_f32 v[38:39], v[38:39], v[202:203]
	v_pk_add_f32 v[40:41], v[40:41], v[204:205]
	v_pk_add_f32 v[34:35], v[34:35], v[206:207]
	v_pk_add_f32 v[36:37], v[36:37], v[208:209]
	v_add_u32_e32 v246, 0x90000, v243
	global_store_dwordx4 v246, v[46:49], s[16:17]
	global_store_dwordx4 v246, v[42:45], s[16:17] offset:16
	global_store_dwordx4 v246, v[38:41], s[16:17] offset:512
	global_store_dwordx4 v246, v[34:37], s[16:17] offset:528
	v_cvt_pk_bf16_f32 v194, v46, v47
	v_cvt_pk_bf16_f32 v195, v48, v49
	v_cvt_pk_bf16_f32 v196, v42, v43
	v_cvt_pk_bf16_f32 v197, v44, v45
	v_cvt_pk_bf16_f32 v198, v38, v39
	v_cvt_pk_bf16_f32 v199, v40, v41
	v_cvt_pk_bf16_f32 v200, v34, v35
	v_cvt_pk_bf16_f32 v201, v36, v37
	v_mul_f32_e32 v202, v47, v47
	v_mul_f32_e32 v203, v49, v49
	v_mul_f32_e32 v204, v43, v43
	v_mul_f32_e32 v205, v45, v45
	v_fmac_f32_e32 v202, v46, v46
	v_fmac_f32_e32 v203, v48, v48
	v_fmac_f32_e32 v204, v42, v42
	v_fmac_f32_e32 v205, v44, v44
	v_add_f32_e32 v202, v202, v203
	v_add_f32_e32 v204, v204, v205
	v_add_f32_e32 v247, v202, v204
	v_mul_f32_e32 v202, v39, v39
	v_mul_f32_e32 v203, v41, v41
	v_mul_f32_e32 v204, v35, v35
	v_mul_f32_e32 v205, v37, v37
	v_fmac_f32_e32 v202, v38, v38
	v_fmac_f32_e32 v203, v40, v40
	v_fmac_f32_e32 v204, v34, v34
	v_fmac_f32_e32 v205, v36, v36
	v_add_f32_e32 v202, v202, v203
	v_add_f32_e32 v204, v204, v205
	v_add_f32_e32 v202, v202, v204
	v_add_f32_e32 v247, v247, v202
	v_add_u32_e32 v246, 0x48000, v242
	global_store_dwordx4 v246, v[194:197], s[64:65]
	global_store_dwordx4 v246, v[198:201], s[64:65] offset:256
	v_mov_b32_e32 v248, v247
	s_nop 1
	v_permlane16_swap_b32_e32 v247, v248
	v_add_f32_e32 v247, v247, v248
	v_mov_b32_e32 v248, v247
	s_nop 1
	v_permlane32_swap_b32_e32 v247, v248
	v_add_f32_e32 v247, v247, v248
	s_mov_b64 exec, s[0:1]
	global_atomic_add_f32 v251, v247, s[10:11] offset:576
	s_mov_b64 exec, -1
	s_waitcnt vmcnt(4)
; #define PG8_BAR __builtin_amdgcn_s_barrier()
; __device__ __forceinline__ unsigned pk(float lo, float hi) { return pg8::cvt_pk_bf16(lo, hi); }
; __device__ __forceinline__ float dot4(f32x4 v) { return (v[0] * v[0] + v[1] * v[1]) + (v[2] * v[2] + v[3] * v[3]); }
; template <class Epi, class Sched, bool ALIGN_EPI = false, bool SP2 = false>
; __device__ __forceinline__ void gemm_phase(PG8_LAS unsigned char* lds, const Gemm g, const Sched& S, const Epi& E) {
;     ...
;         if (!has_next) break;
; #pragma unroll
;         for (int a = 0; a < 2; ++a)
; #pragma unroll
;             for (int b = 0; b < 2; ++b)
; #pragma unroll
;                 for (int m = 0; m < 4; ++m)
; #pragma unroll
;                     for (int n = 0; n < 2; ++n) acc[a][b][m][n] = (f32x4){0.f, 0.f, 0.f, 0.f};
;         cur = nxt; cA = nA; cB = nB; ++ui;
;         if constexpr (ALIGN_EPI) { if (wr == 1) PG8_BAR; }
;     }
;     __device__ __forceinline__ void operator()(const pg8::f32x4 (&acc)[2][2][4][2], const pg8::Unit& u, int wr, int wc, int fr, int fq) const {
;     ...
;             for (int m = 0; m < 4; ++m) {
;                 const int row = row0 + ai * 128 + m * 16;
;                 const float* xi = (row < MP) ? xin_p + (size_t)row * DM : xin_s + (size_t)(row - MP) * DM;
;                 float sq = 0.f;
; #pragma unroll
;                 for (int bj = 0; bj < 2; ++bj) { const int col = u.pn * 256 + bj * 128 + wc * 32 + 8 * fq;
;                     const f32x4 a0 = *(const f32x4*)(xi + col) + acc[ai][bj][m][0], a1 = *(const f32x4*)(xi + col + 4) + acc[ai][bj][m][1];
;                     *(f32x4*)(xout + (size_t)row * DM + col) = a0; *(f32x4*)(xout + (size_t)row * DM + col + 4) = a1;
;                     u32x4 w; w.x = pk(a0[0], a0[1]); w.y = pk(a0[2], a0[3]); w.z = pk(a1[0], a1[1]); w.w = pk(a1[2], a1[3]);
;                     *(u32x4*)(xb + (size_t)row * DM + col) = w;
;                     sq += dot4(a0) + dot4(a1); }
;                 sq += __shfl_xor(sq, 16); sq += __shfl_xor(sq, 32);
;                 if (fq == 0) atomicAdd(ssout + row, sq);
;             }
;     }
	v_pk_add_f32 v[30:31], v[30:31], v[210:211]
	v_pk_add_f32 v[32:33], v[32:33], v[212:213]
	v_pk_add_f32 v[26:27], v[26:27], v[214:215]
	v_pk_add_f32 v[28:29], v[28:29], v[216:217]
	v_pk_add_f32 v[22:23], v[22:23], v[218:219]
	v_pk_add_f32 v[24:25], v[24:25], v[220:221]
	v_pk_add_f32 v[18:19], v[18:19], v[222:223]
	v_pk_add_f32 v[20:21], v[20:21], v[224:225]
	v_add_u32_e32 v246, 0xa0000, v243
	global_store_dwordx4 v246, v[30:33], s[16:17]
	global_store_dwordx4 v246, v[26:29], s[16:17] offset:16
	global_store_dwordx4 v246, v[22:25], s[16:17] offset:512
	global_store_dwordx4 v246, v[18:21], s[16:17] offset:528
	v_cvt_pk_bf16_f32 v210, v30, v31
	v_cvt_pk_bf16_f32 v211, v32, v33
	v_cvt_pk_bf16_f32 v212, v26, v27
	v_cvt_pk_bf16_f32 v213, v28, v29
	v_cvt_pk_bf16_f32 v214, v22, v23
	v_cvt_pk_bf16_f32 v215, v24, v25
	v_cvt_pk_bf16_f32 v216, v18, v19
	v_cvt_pk_bf16_f32 v217, v20, v21
	v_mul_f32_e32 v218, v31, v31
	v_mul_f32_e32 v219, v33, v33
	v_mul_f32_e32 v220, v27, v27
	v_mul_f32_e32 v221, v29, v29
	v_fmac_f32_e32 v218, v30, v30
	v_fmac_f32_e32 v219, v32, v32
	v_fmac_f32_e32 v220, v26, v26
	v_fmac_f32_e32 v221, v28, v28
	v_add_f32_e32 v218, v218, v219
	v_add_f32_e32 v220, v220, v221
	v_add_f32_e32 v247, v218, v220
	v_mul_f32_e32 v218, v23, v23
	v_mul_f32_e32 v219, v25, v25
	v_mul_f32_e32 v220, v19, v19
	v_mul_f32_e32 v221, v21, v21
	v_fmac_f32_e32 v218, v22, v22
	v_fmac_f32_e32 v219, v24, v24
	v_fmac_f32_e32 v220, v18, v18
	v_fmac_f32_e32 v221, v20, v20
	v_add_f32_e32 v218, v218, v219
	v_add_f32_e32 v220, v220, v221
	v_add_f32_e32 v218, v218, v220
	v_add_f32_e32 v247, v247, v218
	v_add_u32_e32 v246, 0x50000, v242
	global_store_dwordx4 v246, v[210:213], s[64:65]
	global_store_dwordx4 v246, v[214:217], s[64:65] offset:256
	v_mov_b32_e32 v248, v247
	s_nop 1
	v_permlane16_swap_b32_e32 v247, v248
	v_add_f32_e32 v247, v247, v248
	v_mov_b32_e32 v248, v247
	s_nop 1
	v_permlane32_swap_b32_e32 v247, v248
	v_add_f32_e32 v247, v247, v248
	s_mov_b64 exec, s[0:1]
	global_atomic_add_f32 v251, v247, s[10:11] offset:640
	s_mov_b64 exec, -1
	s_waitcnt vmcnt(0)
	v_pk_add_f32 v[14:15], v[14:15], v[226:227]
	v_pk_add_f32 v[16:17], v[16:17], v[228:229]
	v_pk_add_f32 v[10:11], v[10:11], v[230:231]
	v_pk_add_f32 v[12:13], v[12:13], v[232:233]
	v_pk_add_f32 v[6:7], v[6:7], v[234:235]
	v_pk_add_f32 v[8:9], v[8:9], v[236:237]
	v_pk_add_f32 v[2:3], v[2:3], v[238:239]
	v_pk_add_f32 v[4:5], v[4:5], v[240:241]
	v_add_u32_e32 v246, 0xb0000, v243
	global_store_dwordx4 v246, v[14:17], s[16:17]
	global_store_dwordx4 v246, v[10:13], s[16:17] offset:16
	global_store_dwordx4 v246, v[6:9], s[16:17] offset:512
	global_store_dwordx4 v246, v[2:5], s[16:17] offset:528
	v_cvt_pk_bf16_f32 v226, v14, v15
	v_cvt_pk_bf16_f32 v227, v16, v17
	v_cvt_pk_bf16_f32 v228, v10, v11
	v_cvt_pk_bf16_f32 v229, v12, v13
	v_cvt_pk_bf16_f32 v230, v6, v7
	v_cvt_pk_bf16_f32 v231, v8, v9
	v_cvt_pk_bf16_f32 v232, v2, v3
	v_cvt_pk_bf16_f32 v233, v4, v5
	v_mul_f32_e32 v234, v15, v15
	v_mul_f32_e32 v235, v17, v17
	v_mul_f32_e32 v236, v11, v11
	v_mul_f32_e32 v237, v13, v13
	v_fmac_f32_e32 v234, v14, v14
	v_fmac_f32_e32 v235, v16, v16
	v_fmac_f32_e32 v236, v10, v10
	v_fmac_f32_e32 v237, v12, v12
	v_add_f32_e32 v234, v234, v235
	v_add_f32_e32 v236, v236, v237
	v_add_f32_e32 v247, v234, v236
	v_mul_f32_e32 v234, v7, v7
	v_mul_f32_e32 v235, v9, v9
	v_mul_f32_e32 v236, v3, v3
	v_mul_f32_e32 v237, v5, v5
	v_fmac_f32_e32 v234, v6, v6
	v_fmac_f32_e32 v235, v8, v8
	v_fmac_f32_e32 v236, v2, v2
	v_fmac_f32_e32 v237, v4, v4
	v_add_f32_e32 v234, v234, v235
	v_add_f32_e32 v236, v236, v237
	v_add_f32_e32 v234, v234, v236
	v_add_f32_e32 v247, v247, v234
	v_add_u32_e32 v246, 0x58000, v242
	global_store_dwordx4 v246, v[226:229], s[64:65]
	global_store_dwordx4 v246, v[230:233], s[64:65] offset:256
	v_mov_b32_e32 v248, v247
	s_nop 1
	v_permlane16_swap_b32_e32 v247, v248
	v_add_f32_e32 v247, v247, v248
	v_mov_b32_e32 v248, v247
	s_nop 1
	v_permlane32_swap_b32_e32 v247, v248
	v_add_f32_e32 v247, v247, v248
	s_mov_b64 exec, s[0:1]
	global_atomic_add_f32 v251, v247, s[10:11] offset:704
	s_mov_b64 exec, -1
	s_and_b64 vcc, exec, s[4:5]
	s_mov_b64 s[4:5], -1
	s_cbranch_vccnz .LBB0_1052
	s_andn2_b64 vcc, exec, s[14:15]
	s_cbranch_vccnz .LBB0_1051
	s_barrier
	s_branch .LBB0_1051

; __device__ __forceinline__ unsigned pk(float lo, float hi) { return pg8::cvt_pk_bf16(lo, hi); }
; __device__ __forceinline__ float dot4(f32x4 v) { return (v[0] * v[0] + v[1] * v[1]) + (v[2] * v[2] + v[3] * v[3]); }
;     __device__ __forceinline__ void operator()(const pg8::f32x4 (&acc)[2][2][4][2], const pg8::Unit& u, int wr, int wc, int fr, int fq) const {
;         const int row0 = u.pm * 256 + wr * 64 + fr;
; #pragma unroll
;         for (int ai = 0; ai < 2; ++ai)
; #pragma unroll
;             for (int m = 0; m < 4; ++m) {
;                 const int row = row0 + ai * 128 + m * 16;
;                 const float* xi = (row < MP) ? xin_p + (size_t)row * DM : xin_s + (size_t)(row - MP) * DM;
;                 float sq = 0.f;
; #pragma unroll
;                 for (int bj = 0; bj < 2; ++bj) { const int col = u.pn * 256 + bj * 128 + wc * 32 + 8 * fq;
;                     const f32x4 a0 = *(const f32x4*)(xi + col) + acc[ai][bj][m][0], a1 = *(const f32x4*)(xi + col + 4) + acc[ai][bj][m][1];
;                     *(f32x4*)(xout + (size_t)row * DM + col) = a0; *(f32x4*)(xout + (size_t)row * DM + col + 4) = a1;
;                     u32x4 w; w.x = pk(a0[0], a0[1]); w.y = pk(a0[2], a0[3]); w.z = pk(a1[0], a1[1]); w.w = pk(a1[2], a1[3]);
;                     *(u32x4*)(xb + (size_t)row * DM + col) = w;
;                     sq += dot4(a0) + dot4(a1); }
;                 sq += __shfl_xor(sq, 16); sq += __shfl_xor(sq, 32);
;                 if (fq == 0) atomicAdd(ssout + row, sq);
.LBB0_1823:
	s_cmp_lt_u32 s40, 64
	s_cselect_b32 s98, s16, s8
	s_cselect_b32 s99, s17, s9
	s_cselect_b32 s100, 0, 0x4000
	v_lshl_add_u32 v138, s40, 8, v156
	v_lshl_or_b32 v163, s38, 8, v158
	v_lshlrev_b32_e32 v236, 2, v138
	v_lshlrev_b32_e32 v183, 1, v163
	v_lshl_add_u32 v237, v138, 11, v183
	v_lshlrev_b32_e32 v183, 2, v163
	v_lshl_add_u32 v238, v138, 12, v183
	v_subrev_u32_e32 v138, s100, v138
	v_lshl_add_u32 v239, v138, 12, v183
	global_load_dwordx4 v[148:151], v239, s[98:99]
	global_load_dwordx4 v[152:155], v239, s[98:99] offset:16
	global_load_dwordx4 v[164:167], v239, s[98:99] offset:512
	global_load_dwordx4 v[184:187], v239, s[98:99] offset:528
	v_add_u32_e32 v240, 0x10000, v239
	global_load_dwordx4 v[188:191], v240, s[98:99]
	global_load_dwordx4 v[192:195], v240, s[98:99] offset:16
	global_load_dwordx4 v[196:199], v240, s[98:99] offset:512
	global_load_dwordx4 v[200:203], v240, s[98:99] offset:528
	v_add_u32_e32 v240, 0x20000, v239
	global_load_dwordx4 v[204:207], v240, s[98:99]
	global_load_dwordx4 v[208:211], v240, s[98:99] offset:16
	global_load_dwordx4 v[212:215], v240, s[98:99] offset:512
	global_load_dwordx4 v[216:219], v240, s[98:99] offset:528
	v_add_u32_e32 v240, 0x30000, v239
	global_load_dwordx4 v[220:223], v240, s[98:99]
	global_load_dwordx4 v[224:227], v240, s[98:99] offset:16
	global_load_dwordx4 v[228:231], v240, s[98:99] offset:512
	global_load_dwordx4 v[232:235], v240, s[98:99] offset:528
	s_waitcnt vmcnt(12)
	v_pk_add_f32 v[126:127], v[126:127], v[148:149]
	v_pk_add_f32 v[128:129], v[128:129], v[150:151]
	v_pk_add_f32 v[122:123], v[122:123], v[152:153]
	v_pk_add_f32 v[124:125], v[124:125], v[154:155]
	v_pk_add_f32 v[118:119], v[118:119], v[164:165]
	v_pk_add_f32 v[120:121], v[120:121], v[166:167]
	v_pk_add_f32 v[114:115], v[114:115], v[184:185]
	v_pk_add_f32 v[116:117], v[116:117], v[186:187]
	global_store_dwordx4 v238, v[126:129], s[16:17]
	global_store_dwordx4 v238, v[122:125], s[16:17] offset:16
	global_store_dwordx4 v238, v[118:121], s[16:17] offset:512
	global_store_dwordx4 v238, v[114:117], s[16:17] offset:528
	v_cvt_pk_bf16_f32 v148, v126, v127
	v_cvt_pk_bf16_f32 v149, v128, v129
	v_cvt_pk_bf16_f32 v150, v122, v123
	v_cvt_pk_bf16_f32 v151, v124, v125
	v_cvt_pk_bf16_f32 v152, v118, v119
	v_cvt_pk_bf16_f32 v153, v120, v121
	v_cvt_pk_bf16_f32 v154, v114, v115
	v_cvt_pk_bf16_f32 v155, v116, v117
	v_mul_f32_e32 v164, v127, v127
	v_mul_f32_e32 v165, v129, v129
	v_mul_f32_e32 v166, v123, v123
	v_mul_f32_e32 v167, v125, v125
	v_fmac_f32_e32 v164, v126, v126
	v_fmac_f32_e32 v165, v128, v128
	v_fmac_f32_e32 v166, v122, v122
	v_fmac_f32_e32 v167, v124, v124
	v_add_f32_e32 v164, v164, v165
	v_add_f32_e32 v166, v166, v167
	v_add_f32_e32 v242, v164, v166
	v_mul_f32_e32 v164, v119, v119
	v_mul_f32_e32 v165, v121, v121
	v_mul_f32_e32 v166, v115, v115
	v_mul_f32_e32 v167, v117, v117
	v_fmac_f32_e32 v164, v118, v118
	v_fmac_f32_e32 v165, v120, v120
	v_fmac_f32_e32 v166, v114, v114
	v_fmac_f32_e32 v167, v116, v116
	v_add_f32_e32 v164, v164, v165
	v_add_f32_e32 v166, v166, v167
	v_add_f32_e32 v164, v164, v166
	v_add_f32_e32 v242, v242, v164
	global_store_dwordx4 v237, v[148:151], s[64:65]
	global_store_dwordx4 v237, v[152:155], s[64:65] offset:256
	v_mov_b32_e32 v243, v242
	s_nop 1
	v_permlane16_swap_b32_e32 v242, v243
	v_add_f32_e32 v242, v242, v243
	v_mov_b32_e32 v243, v242
	s_nop 1
	v_permlane32_swap_b32_e32 v242, v243
	v_add_f32_e32 v242, v242, v243
	s_mov_b64 exec, s[0:1]
	global_atomic_add_f32 v236, v242, s[10:11]
	s_mov_b64 exec, -1
	v_add_u32_e32 v240, 0x80000, v239
	global_load_dwordx4 v[148:151], v240, s[98:99]
	global_load_dwordx4 v[152:155], v240, s[98:99] offset:16
	global_load_dwordx4 v[164:167], v240, s[98:99] offset:512
	global_load_dwordx4 v[184:187], v240, s[98:99] offset:528
	s_waitcnt vmcnt(12)
	v_pk_add_f32 v[110:111], v[110:111], v[188:189]
	v_pk_add_f32 v[112:113], v[112:113], v[190:191]
	v_pk_add_f32 v[106:107], v[106:107], v[192:193]
	v_pk_add_f32 v[108:109], v[108:109], v[194:195]
	v_pk_add_f32 v[102:103], v[102:103], v[196:197]
	v_pk_add_f32 v[104:105], v[104:105], v[198:199]
	v_pk_add_f32 v[98:99], v[98:99], v[200:201]
	v_pk_add_f32 v[100:101], v[100:101], v[202:203]
	v_add_u32_e32 v241, 0x10000, v238
	global_store_dwordx4 v241, v[110:113], s[16:17]
	global_store_dwordx4 v241, v[106:109], s[16:17] offset:16
	global_store_dwordx4 v241, v[102:105], s[16:17] offset:512
	global_store_dwordx4 v241, v[98:101], s[16:17] offset:528
	v_cvt_pk_bf16_f32 v188, v110, v111
	v_cvt_pk_bf16_f32 v189, v112, v113
	v_cvt_pk_bf16_f32 v190, v106, v107
	v_cvt_pk_bf16_f32 v191, v108, v109
	v_cvt_pk_bf16_f32 v192, v102, v103
	v_cvt_pk_bf16_f32 v193, v104, v105
	v_cvt_pk_bf16_f32 v194, v98, v99
	v_cvt_pk_bf16_f32 v195, v100, v101
	v_mul_f32_e32 v196, v111, v111
	v_mul_f32_e32 v197, v113, v113
	v_mul_f32_e32 v198, v107, v107
	v_mul_f32_e32 v199, v109, v109
	v_fmac_f32_e32 v196, v110, v110
	v_fmac_f32_e32 v197, v112, v112
	v_fmac_f32_e32 v198, v106, v106
	v_fmac_f32_e32 v199, v108, v108
	v_add_f32_e32 v196, v196, v197
	v_add_f32_e32 v198, v198, v199
	v_add_f32_e32 v242, v196, v198
	v_mul_f32_e32 v196, v103, v103
	v_mul_f32_e32 v197, v105, v105
	v_mul_f32_e32 v198, v99, v99
	v_mul_f32_e32 v199, v101, v101
	v_fmac_f32_e32 v196, v102, v102
	v_fmac_f32_e32 v197, v104, v104
	v_fmac_f32_e32 v198, v98, v98
	v_fmac_f32_e32 v199, v100, v100
	v_add_f32_e32 v196, v196, v197
	v_add_f32_e32 v198, v198, v199
	v_add_f32_e32 v196, v196, v198
	v_add_f32_e32 v242, v242, v196
	v_add_u32_e32 v241, 0x8000, v237
	global_store_dwordx4 v241, v[188:191], s[64:65]
	global_store_dwordx4 v241, v[192:195], s[64:65] offset:256
	v_mov_b32_e32 v243, v242
	s_nop 1
	v_permlane16_swap_b32_e32 v242, v243
	v_add_f32_e32 v242, v242, v243
	v_mov_b32_e32 v243, v242
	s_nop 1
	v_permlane32_swap_b32_e32 v242, v243
	v_add_f32_e32 v242, v242, v243
	s_mov_b64 exec, s[0:1]
	global_atomic_add_f32 v236, v242, s[10:11] offset:64
	s_mov_b64 exec, -1
	v_add_u32_e32 v240, 0x90000, v239
	global_load_dwordx4 v[188:191], v240, s[98:99]
	global_load_dwordx4 v[192:195], v240, s[98:99] offset:16
	global_load_dwordx4 v[196:199], v240, s[98:99] offset:512
	global_load_dwordx4 v[200:203], v240, s[98:99] offset:528
	s_waitcnt vmcnt(12)
; __device__ __forceinline__ unsigned pk(float lo, float hi) { return pg8::cvt_pk_bf16(lo, hi); }
; __device__ __forceinline__ float dot4(f32x4 v) { return (v[0] * v[0] + v[1] * v[1]) + (v[2] * v[2] + v[3] * v[3]); }
;     __device__ __forceinline__ void operator()(const pg8::f32x4 (&acc)[2][2][4][2], const pg8::Unit& u, int wr, int wc, int fr, int fq) const {
;     ...
;             for (int m = 0; m < 4; ++m) {
;                 const int row = row0 + ai * 128 + m * 16;
;                 const float* xi = (row < MP) ? xin_p + (size_t)row * DM : xin_s + (size_t)(row - MP) * DM;
;                 float sq = 0.f;
; #pragma unroll
;                 for (int bj = 0; bj < 2; ++bj) { const int col = u.pn * 256 + bj * 128 + wc * 32 + 8 * fq;
;                     const f32x4 a0 = *(const f32x4*)(xi + col) + acc[ai][bj][m][0], a1 = *(const f32x4*)(xi + col + 4) + acc[ai][bj][m][1];
;                     *(f32x4*)(xout + (size_t)row * DM + col) = a0; *(f32x4*)(xout + (size_t)row * DM + col + 4) = a1;
;                     u32x4 w; w.x = pk(a0[0], a0[1]); w.y = pk(a0[2], a0[3]); w.z = pk(a1[0], a1[1]); w.w = pk(a1[2], a1[3]);
;                     *(u32x4*)(xb + (size_t)row * DM + col) = w;
;                     sq += dot4(a0) + dot4(a1); }
;                 sq += __shfl_xor(sq, 16); sq += __shfl_xor(sq, 32);
;                 if (fq == 0) atomicAdd(ssout + row, sq);
	v_pk_add_f32 v[94:95], v[94:95], v[204:205]
	v_pk_add_f32 v[96:97], v[96:97], v[206:207]
	v_pk_add_f32 v[90:91], v[90:91], v[208:209]
	v_pk_add_f32 v[92:93], v[92:93], v[210:211]
	v_pk_add_f32 v[86:87], v[86:87], v[212:213]
	v_pk_add_f32 v[88:89], v[88:89], v[214:215]
	v_pk_add_f32 v[82:83], v[82:83], v[216:217]
	v_pk_add_f32 v[84:85], v[84:85], v[218:219]
	v_add_u32_e32 v241, 0x20000, v238
	global_store_dwordx4 v241, v[94:97], s[16:17]
	global_store_dwordx4 v241, v[90:93], s[16:17] offset:16
	global_store_dwordx4 v241, v[86:89], s[16:17] offset:512
	global_store_dwordx4 v241, v[82:85], s[16:17] offset:528
	v_cvt_pk_bf16_f32 v204, v94, v95
	v_cvt_pk_bf16_f32 v205, v96, v97
	v_cvt_pk_bf16_f32 v206, v90, v91
	v_cvt_pk_bf16_f32 v207, v92, v93
	v_cvt_pk_bf16_f32 v208, v86, v87
	v_cvt_pk_bf16_f32 v209, v88, v89
	v_cvt_pk_bf16_f32 v210, v82, v83
	v_cvt_pk_bf16_f32 v211, v84, v85
	v_mul_f32_e32 v212, v95, v95
	v_mul_f32_e32 v213, v97, v97
	v_mul_f32_e32 v214, v91, v91
	v_mul_f32_e32 v215, v93, v93
	v_fmac_f32_e32 v212, v94, v94
	v_fmac_f32_e32 v213, v96, v96
	v_fmac_f32_e32 v214, v90, v90
	v_fmac_f32_e32 v215, v92, v92
	v_add_f32_e32 v212, v212, v213
	v_add_f32_e32 v214, v214, v215
	v_add_f32_e32 v242, v212, v214
	v_mul_f32_e32 v212, v87, v87
	v_mul_f32_e32 v213, v89, v89
	v_mul_f32_e32 v214, v83, v83
	v_mul_f32_e32 v215, v85, v85
	v_fmac_f32_e32 v212, v86, v86
	v_fmac_f32_e32 v213, v88, v88
	v_fmac_f32_e32 v214, v82, v82
	v_fmac_f32_e32 v215, v84, v84
	v_add_f32_e32 v212, v212, v213
	v_add_f32_e32 v214, v214, v215
	v_add_f32_e32 v212, v212, v214
	v_add_f32_e32 v242, v242, v212
	v_add_u32_e32 v241, 0x10000, v237
	global_store_dwordx4 v241, v[204:207], s[64:65]
	global_store_dwordx4 v241, v[208:211], s[64:65] offset:256
	v_mov_b32_e32 v243, v242
	s_nop 1
	v_permlane16_swap_b32_e32 v242, v243
	v_add_f32_e32 v242, v242, v243
	v_mov_b32_e32 v243, v242
	s_nop 1
	v_permlane32_swap_b32_e32 v242, v243
	v_add_f32_e32 v242, v242, v243
	s_mov_b64 exec, s[0:1]
	global_atomic_add_f32 v236, v242, s[10:11] offset:128
	s_mov_b64 exec, -1
	v_add_u32_e32 v240, 0xa0000, v239
	global_load_dwordx4 v[204:207], v240, s[98:99]
	global_load_dwordx4 v[208:211], v240, s[98:99] offset:16
	global_load_dwordx4 v[212:215], v240, s[98:99] offset:512
	global_load_dwordx4 v[216:219], v240, s[98:99] offset:528
	s_waitcnt vmcnt(12)
	v_pk_add_f32 v[78:79], v[78:79], v[220:221]
	v_pk_add_f32 v[80:81], v[80:81], v[222:223]
	v_pk_add_f32 v[74:75], v[74:75], v[224:225]
	v_pk_add_f32 v[76:77], v[76:77], v[226:227]
	v_pk_add_f32 v[70:71], v[70:71], v[228:229]
	v_pk_add_f32 v[72:73], v[72:73], v[230:231]
	v_pk_add_f32 v[66:67], v[66:67], v[232:233]
	v_pk_add_f32 v[68:69], v[68:69], v[234:235]
	v_add_u32_e32 v241, 0x30000, v238
	global_store_dwordx4 v241, v[78:81], s[16:17]
	global_store_dwordx4 v241, v[74:77], s[16:17] offset:16
	global_store_dwordx4 v241, v[70:73], s[16:17] offset:512
	global_store_dwordx4 v241, v[66:69], s[16:17] offset:528
	v_cvt_pk_bf16_f32 v220, v78, v79
	v_cvt_pk_bf16_f32 v221, v80, v81
	v_cvt_pk_bf16_f32 v222, v74, v75
	v_cvt_pk_bf16_f32 v223, v76, v77
	v_cvt_pk_bf16_f32 v224, v70, v71
	v_cvt_pk_bf16_f32 v225, v72, v73
	v_cvt_pk_bf16_f32 v226, v66, v67
	v_cvt_pk_bf16_f32 v227, v68, v69
	v_mul_f32_e32 v228, v79, v79
	v_mul_f32_e32 v229, v81, v81
	v_mul_f32_e32 v230, v75, v75
	v_mul_f32_e32 v231, v77, v77
	v_fmac_f32_e32 v228, v78, v78
	v_fmac_f32_e32 v229, v80, v80
	v_fmac_f32_e32 v230, v74, v74
	v_fmac_f32_e32 v231, v76, v76
	v_add_f32_e32 v228, v228, v229
	v_add_f32_e32 v230, v230, v231
	v_add_f32_e32 v242, v228, v230
	v_mul_f32_e32 v228, v71, v71
	v_mul_f32_e32 v229, v73, v73
	v_mul_f32_e32 v230, v67, v67
	v_mul_f32_e32 v231, v69, v69
	v_fmac_f32_e32 v228, v70, v70
	v_fmac_f32_e32 v229, v72, v72
	v_fmac_f32_e32 v230, v66, v66
	v_fmac_f32_e32 v231, v68, v68
	v_add_f32_e32 v228, v228, v229
	v_add_f32_e32 v230, v230, v231
	v_add_f32_e32 v228, v228, v230
	v_add_f32_e32 v242, v242, v228
	v_add_u32_e32 v241, 0x18000, v237
	global_store_dwordx4 v241, v[220:223], s[64:65]
	global_store_dwordx4 v241, v[224:227], s[64:65] offset:256
	v_mov_b32_e32 v243, v242
	s_nop 1
	v_permlane16_swap_b32_e32 v242, v243
	v_add_f32_e32 v242, v242, v243
	v_mov_b32_e32 v243, v242
	s_nop 1
	v_permlane32_swap_b32_e32 v242, v243
	v_add_f32_e32 v242, v242, v243
	s_mov_b64 exec, s[0:1]
	global_atomic_add_f32 v236, v242, s[10:11] offset:192
	s_mov_b64 exec, -1
	v_add_u32_e32 v240, 0xb0000, v239
	global_load_dwordx4 v[220:223], v240, s[98:99]
	global_load_dwordx4 v[224:227], v240, s[98:99] offset:16
	global_load_dwordx4 v[228:231], v240, s[98:99] offset:512
	global_load_dwordx4 v[232:235], v240, s[98:99] offset:528
	s_waitcnt vmcnt(12)
; __device__ __forceinline__ unsigned pk(float lo, float hi) { return pg8::cvt_pk_bf16(lo, hi); }
; __device__ __forceinline__ float dot4(f32x4 v) { return (v[0] * v[0] + v[1] * v[1]) + (v[2] * v[2] + v[3] * v[3]); }
;     __device__ __forceinline__ void operator()(const pg8::f32x4 (&acc)[2][2][4][2], const pg8::Unit& u, int wr, int wc, int fr, int fq) const {
;     ...
;             for (int m = 0; m < 4; ++m) {
;                 const int row = row0 + ai * 128 + m * 16;
;                 const float* xi = (row < MP) ? xin_p + (size_t)row * DM : xin_s + (size_t)(row - MP) * DM;
;                 float sq = 0.f;
; #pragma unroll
;                 for (int bj = 0; bj < 2; ++bj) { const int col = u.pn * 256 + bj * 128 + wc * 32 + 8 * fq;
;                     const f32x4 a0 = *(const f32x4*)(xi + col) + acc[ai][bj][m][0], a1 = *(const f32x4*)(xi + col + 4) + acc[ai][bj][m][1];
;                     *(f32x4*)(xout + (size_t)row * DM + col) = a0; *(f32x4*)(xout + (size_t)row * DM + col + 4) = a1;
;                     u32x4 w; w.x = pk(a0[0], a0[1]); w.y = pk(a0[2], a0[3]); w.z = pk(a1[0], a1[1]); w.w = pk(a1[2], a1[3]);
;                     *(u32x4*)(xb + (size_t)row * DM + col) = w;
;                     sq += dot4(a0) + dot4(a1); }
;                 sq += __shfl_xor(sq, 16); sq += __shfl_xor(sq, 32);
;                 if (fq == 0) atomicAdd(ssout + row, sq);
	v_pk_add_f32 v[62:63], v[62:63], v[148:149]
	v_pk_add_f32 v[64:65], v[64:65], v[150:151]
	v_pk_add_f32 v[58:59], v[58:59], v[152:153]
	v_pk_add_f32 v[60:61], v[60:61], v[154:155]
	v_pk_add_f32 v[54:55], v[54:55], v[164:165]
	v_pk_add_f32 v[56:57], v[56:57], v[166:167]
	v_pk_add_f32 v[50:51], v[50:51], v[184:185]
	v_pk_add_f32 v[52:53], v[52:53], v[186:187]
	v_add_u32_e32 v241, 0x80000, v238
	global_store_dwordx4 v241, v[62:65], s[16:17]
	global_store_dwordx4 v241, v[58:61], s[16:17] offset:16
	global_store_dwordx4 v241, v[54:57], s[16:17] offset:512
	global_store_dwordx4 v241, v[50:53], s[16:17] offset:528
	v_cvt_pk_bf16_f32 v148, v62, v63
	v_cvt_pk_bf16_f32 v149, v64, v65
	v_cvt_pk_bf16_f32 v150, v58, v59
	v_cvt_pk_bf16_f32 v151, v60, v61
	v_cvt_pk_bf16_f32 v152, v54, v55
	v_cvt_pk_bf16_f32 v153, v56, v57
	v_cvt_pk_bf16_f32 v154, v50, v51
	v_cvt_pk_bf16_f32 v155, v52, v53
	v_mul_f32_e32 v164, v63, v63
	v_mul_f32_e32 v165, v65, v65
	v_mul_f32_e32 v166, v59, v59
	v_mul_f32_e32 v167, v61, v61
	v_fmac_f32_e32 v164, v62, v62
	v_fmac_f32_e32 v165, v64, v64
	v_fmac_f32_e32 v166, v58, v58
	v_fmac_f32_e32 v167, v60, v60
	v_add_f32_e32 v164, v164, v165
	v_add_f32_e32 v166, v166, v167
	v_add_f32_e32 v242, v164, v166
	v_mul_f32_e32 v164, v55, v55
	v_mul_f32_e32 v165, v57, v57
	v_mul_f32_e32 v166, v51, v51
	v_mul_f32_e32 v167, v53, v53
	v_fmac_f32_e32 v164, v54, v54
	v_fmac_f32_e32 v165, v56, v56
	v_fmac_f32_e32 v166, v50, v50
	v_fmac_f32_e32 v167, v52, v52
	v_add_f32_e32 v164, v164, v165
	v_add_f32_e32 v166, v166, v167
	v_add_f32_e32 v164, v164, v166
	v_add_f32_e32 v242, v242, v164
	v_add_u32_e32 v241, 0x40000, v237
	global_store_dwordx4 v241, v[148:151], s[64:65]
	global_store_dwordx4 v241, v[152:155], s[64:65] offset:256
	v_mov_b32_e32 v243, v242
	s_nop 1
	v_permlane16_swap_b32_e32 v242, v243
	v_add_f32_e32 v242, v242, v243
	v_mov_b32_e32 v243, v242
	s_nop 1
	v_permlane32_swap_b32_e32 v242, v243
	v_add_f32_e32 v242, v242, v243
	s_mov_b64 exec, s[0:1]
	global_atomic_add_f32 v236, v242, s[10:11] offset:512
	s_mov_b64 exec, -1
	s_waitcnt vmcnt(8)
	v_pk_add_f32 v[46:47], v[46:47], v[188:189]
	v_pk_add_f32 v[48:49], v[48:49], v[190:191]
	v_pk_add_f32 v[42:43], v[42:43], v[192:193]
	v_pk_add_f32 v[44:45], v[44:45], v[194:195]
	v_pk_add_f32 v[38:39], v[38:39], v[196:197]
	v_pk_add_f32 v[40:41], v[40:41], v[198:199]
	v_pk_add_f32 v[34:35], v[34:35], v[200:201]
	v_pk_add_f32 v[36:37], v[36:37], v[202:203]
	v_add_u32_e32 v241, 0x90000, v238
	global_store_dwordx4 v241, v[46:49], s[16:17]
	global_store_dwordx4 v241, v[42:45], s[16:17] offset:16
	global_store_dwordx4 v241, v[38:41], s[16:17] offset:512
	global_store_dwordx4 v241, v[34:37], s[16:17] offset:528
	v_cvt_pk_bf16_f32 v188, v46, v47
	v_cvt_pk_bf16_f32 v189, v48, v49
	v_cvt_pk_bf16_f32 v190, v42, v43
	v_cvt_pk_bf16_f32 v191, v44, v45
	v_cvt_pk_bf16_f32 v192, v38, v39
	v_cvt_pk_bf16_f32 v193, v40, v41
	v_cvt_pk_bf16_f32 v194, v34, v35
	v_cvt_pk_bf16_f32 v195, v36, v37
	v_mul_f32_e32 v196, v47, v47
	v_mul_f32_e32 v197, v49, v49
	v_mul_f32_e32 v198, v43, v43
	v_mul_f32_e32 v199, v45, v45
	v_fmac_f32_e32 v196, v46, v46
	v_fmac_f32_e32 v197, v48, v48
	v_fmac_f32_e32 v198, v42, v42
	v_fmac_f32_e32 v199, v44, v44
	v_add_f32_e32 v196, v196, v197
	v_add_f32_e32 v198, v198, v199
	v_add_f32_e32 v242, v196, v198
	v_mul_f32_e32 v196, v39, v39
	v_mul_f32_e32 v197, v41, v41
	v_mul_f32_e32 v198, v35, v35
	v_mul_f32_e32 v199, v37, v37
	v_fmac_f32_e32 v196, v38, v38
	v_fmac_f32_e32 v197, v40, v40
	v_fmac_f32_e32 v198, v34, v34
	v_fmac_f32_e32 v199, v36, v36
	v_add_f32_e32 v196, v196, v197
	v_add_f32_e32 v198, v198, v199
	v_add_f32_e32 v196, v196, v198
	v_add_f32_e32 v242, v242, v196
	v_add_u32_e32 v241, 0x48000, v237
	global_store_dwordx4 v241, v[188:191], s[64:65]
	global_store_dwordx4 v241, v[192:195], s[64:65] offset:256
	v_mov_b32_e32 v243, v242
	s_nop 1
	v_permlane16_swap_b32_e32 v242, v243
	v_add_f32_e32 v242, v242, v243
	v_mov_b32_e32 v243, v242
	s_nop 1
	v_permlane32_swap_b32_e32 v242, v243
	v_add_f32_e32 v242, v242, v243
	s_mov_b64 exec, s[0:1]
	global_atomic_add_f32 v236, v242, s[10:11] offset:576
	s_mov_b64 exec, -1
	s_waitcnt vmcnt(4)
; #define PG8_BAR __builtin_amdgcn_s_barrier()
; __device__ __forceinline__ unsigned pk(float lo, float hi) { return pg8::cvt_pk_bf16(lo, hi); }
; __device__ __forceinline__ float dot4(f32x4 v) { return (v[0] * v[0] + v[1] * v[1]) + (v[2] * v[2] + v[3] * v[3]); }
; template <class Epi, class Sched, bool ALIGN_EPI = false, bool SP2 = false>
; __device__ __forceinline__ void gemm_phase(PG8_LAS unsigned char* lds, const Gemm g, const Sched& S, const Epi& E) {
;     ...
;         if (!has_next) break;
; #pragma unroll
;         for (int a = 0; a < 2; ++a)
; #pragma unroll
;             for (int b = 0; b < 2; ++b)
; #pragma unroll
;                 for (int m = 0; m < 4; ++m)
; #pragma unroll
;                     for (int n = 0; n < 2; ++n) acc[a][b][m][n] = (f32x4){0.f, 0.f, 0.f, 0.f};
;         cur = nxt; cA = nA; cB = nB; ++ui;
;         if constexpr (ALIGN_EPI) { if (wr == 1) PG8_BAR; }
;     }
;     __device__ __forceinline__ void operator()(const pg8::f32x4 (&acc)[2][2][4][2], const pg8::Unit& u, int wr, int wc, int fr, int fq) const {
;     ...
;             for (int m = 0; m < 4; ++m) {
;                 const int row = row0 + ai * 128 + m * 16;
;                 const float* xi = (row < MP) ? xin_p + (size_t)row * DM : xin_s + (size_t)(row - MP) * DM;
;                 float sq = 0.f;
; #pragma unroll
;                 for (int bj = 0; bj < 2; ++bj) { const int col = u.pn * 256 + bj * 128 + wc * 32 + 8 * fq;
;                     const f32x4 a0 = *(const f32x4*)(xi + col) + acc[ai][bj][m][0], a1 = *(const f32x4*)(xi + col + 4) + acc[ai][bj][m][1];
;                     *(f32x4*)(xout + (size_t)row * DM + col) = a0; *(f32x4*)(xout + (size_t)row * DM + col + 4) = a1;
;                     u32x4 w; w.x = pk(a0[0], a0[1]); w.y = pk(a0[2], a0[3]); w.z = pk(a1[0], a1[1]); w.w = pk(a1[2], a1[3]);
;                     *(u32x4*)(xb + (size_t)row * DM + col) = w;
;                     sq += dot4(a0) + dot4(a1); }
;                 sq += __shfl_xor(sq, 16); sq += __shfl_xor(sq, 32);
;                 if (fq == 0) atomicAdd(ssout + row, sq);
;             }
;     }
	v_pk_add_f32 v[30:31], v[30:31], v[204:205]
	v_pk_add_f32 v[32:33], v[32:33], v[206:207]
	v_pk_add_f32 v[26:27], v[26:27], v[208:209]
	v_pk_add_f32 v[28:29], v[28:29], v[210:211]
	v_pk_add_f32 v[22:23], v[22:23], v[212:213]
	v_pk_add_f32 v[24:25], v[24:25], v[214:215]
	v_pk_add_f32 v[18:19], v[18:19], v[216:217]
	v_pk_add_f32 v[20:21], v[20:21], v[218:219]
	v_add_u32_e32 v241, 0xa0000, v238
	global_store_dwordx4 v241, v[30:33], s[16:17]
	global_store_dwordx4 v241, v[26:29], s[16:17] offset:16
	global_store_dwordx4 v241, v[22:25], s[16:17] offset:512
	global_store_dwordx4 v241, v[18:21], s[16:17] offset:528
	v_cvt_pk_bf16_f32 v204, v30, v31
	v_cvt_pk_bf16_f32 v205, v32, v33
	v_cvt_pk_bf16_f32 v206, v26, v27
	v_cvt_pk_bf16_f32 v207, v28, v29
	v_cvt_pk_bf16_f32 v208, v22, v23
	v_cvt_pk_bf16_f32 v209, v24, v25
	v_cvt_pk_bf16_f32 v210, v18, v19
	v_cvt_pk_bf16_f32 v211, v20, v21
	v_mul_f32_e32 v212, v31, v31
	v_mul_f32_e32 v213, v33, v33
	v_mul_f32_e32 v214, v27, v27
	v_mul_f32_e32 v215, v29, v29
	v_fmac_f32_e32 v212, v30, v30
	v_fmac_f32_e32 v213, v32, v32
	v_fmac_f32_e32 v214, v26, v26
	v_fmac_f32_e32 v215, v28, v28
	v_add_f32_e32 v212, v212, v213
	v_add_f32_e32 v214, v214, v215
	v_add_f32_e32 v242, v212, v214
	v_mul_f32_e32 v212, v23, v23
	v_mul_f32_e32 v213, v25, v25
	v_mul_f32_e32 v214, v19, v19
	v_mul_f32_e32 v215, v21, v21
	v_fmac_f32_e32 v212, v22, v22
	v_fmac_f32_e32 v213, v24, v24
	v_fmac_f32_e32 v214, v18, v18
	v_fmac_f32_e32 v215, v20, v20
	v_add_f32_e32 v212, v212, v213
	v_add_f32_e32 v214, v214, v215
	v_add_f32_e32 v212, v212, v214
	v_add_f32_e32 v242, v242, v212
	v_add_u32_e32 v241, 0x50000, v237
	global_store_dwordx4 v241, v[204:207], s[64:65]
	global_store_dwordx4 v241, v[208:211], s[64:65] offset:256
	v_mov_b32_e32 v243, v242
	s_nop 1
	v_permlane16_swap_b32_e32 v242, v243
	v_add_f32_e32 v242, v242, v243
	v_mov_b32_e32 v243, v242
	s_nop 1
	v_permlane32_swap_b32_e32 v242, v243
	v_add_f32_e32 v242, v242, v243
	s_mov_b64 exec, s[0:1]
	global_atomic_add_f32 v236, v242, s[10:11] offset:640
	s_mov_b64 exec, -1
	s_waitcnt vmcnt(0)
	v_pk_add_f32 v[14:15], v[14:15], v[220:221]
	v_pk_add_f32 v[16:17], v[16:17], v[222:223]
	v_pk_add_f32 v[10:11], v[10:11], v[224:225]
	v_pk_add_f32 v[12:13], v[12:13], v[226:227]
	v_pk_add_f32 v[6:7], v[6:7], v[228:229]
	v_pk_add_f32 v[8:9], v[8:9], v[230:231]
	v_pk_add_f32 v[2:3], v[2:3], v[232:233]
	v_pk_add_f32 v[4:5], v[4:5], v[234:235]
	v_add_u32_e32 v241, 0xb0000, v238
	global_store_dwordx4 v241, v[14:17], s[16:17]
	global_store_dwordx4 v241, v[10:13], s[16:17] offset:16
	global_store_dwordx4 v241, v[6:9], s[16:17] offset:512
	global_store_dwordx4 v241, v[2:5], s[16:17] offset:528
	v_cvt_pk_bf16_f32 v220, v14, v15
	v_cvt_pk_bf16_f32 v221, v16, v17
	v_cvt_pk_bf16_f32 v222, v10, v11
	v_cvt_pk_bf16_f32 v223, v12, v13
	v_cvt_pk_bf16_f32 v224, v6, v7
	v_cvt_pk_bf16_f32 v225, v8, v9
	v_cvt_pk_bf16_f32 v226, v2, v3
	v_cvt_pk_bf16_f32 v227, v4, v5
	v_mul_f32_e32 v228, v15, v15
	v_mul_f32_e32 v229, v17, v17
	v_mul_f32_e32 v230, v11, v11
	v_mul_f32_e32 v231, v13, v13
	v_fmac_f32_e32 v228, v14, v14
	v_fmac_f32_e32 v229, v16, v16
	v_fmac_f32_e32 v230, v10, v10
	v_fmac_f32_e32 v231, v12, v12
	v_add_f32_e32 v228, v228, v229
	v_add_f32_e32 v230, v230, v231
	v_add_f32_e32 v242, v228, v230
	v_mul_f32_e32 v228, v7, v7
	v_mul_f32_e32 v229, v9, v9
	v_mul_f32_e32 v230, v3, v3
	v_mul_f32_e32 v231, v5, v5
	v_fmac_f32_e32 v228, v6, v6
	v_fmac_f32_e32 v229, v8, v8
	v_fmac_f32_e32 v230, v2, v2
	v_fmac_f32_e32 v231, v4, v4
	v_add_f32_e32 v228, v228, v229
	v_add_f32_e32 v230, v230, v231
	v_add_f32_e32 v228, v228, v230
	v_add_f32_e32 v242, v242, v228
	v_add_u32_e32 v241, 0x58000, v237
	global_store_dwordx4 v241, v[220:223], s[64:65]
	global_store_dwordx4 v241, v[224:227], s[64:65] offset:256
	v_mov_b32_e32 v243, v242
	s_nop 1
	v_permlane16_swap_b32_e32 v242, v243
	v_add_f32_e32 v242, v242, v243
	v_mov_b32_e32 v243, v242
	s_nop 1
	v_permlane32_swap_b32_e32 v242, v243
	v_add_f32_e32 v242, v242, v243
	s_mov_b64 exec, s[0:1]
	global_atomic_add_f32 v236, v242, s[10:11] offset:704
	s_mov_b64 exec, -1
	s_andn2_b64 vcc, exec, s[4:5]
	s_mov_b64 s[4:5], -1
	s_cbranch_vccnz .LBB0_1816
	s_andn2_b64 vcc, exec, s[6:7]
	s_cbranch_vccnz .LBB0_1815
	s_barrier
	s_branch .LBB0_1815

; __device__ __forceinline__ unsigned pk(float lo, float hi) { return pg8::cvt_pk_bf16(lo, hi); }
; __device__ __forceinline__ float dot4(f32x4 v) { return (v[0] * v[0] + v[1] * v[1]) + (v[2] * v[2] + v[3] * v[3]); }
;     __device__ __forceinline__ void operator()(const pg8::f32x4 (&acc)[2][2][4][2], const pg8::Unit& u, int wr, int wc, int fr, int fq) const {
;         const int row0 = u.pm * 256 + wr * 64 + fr;
; #pragma unroll
;         for (int ai = 0; ai < 2; ++ai)
; #pragma unroll
;             for (int m = 0; m < 4; ++m) {
;                 const int row = row0 + ai * 128 + m * 16;
;                 const float* xi = (row < MP) ? xin_p + (size_t)row * DM : xin_s + (size_t)(row - MP) * DM;
;                 float sq = 0.f;
; #pragma unroll
;                 for (int bj = 0; bj < 2; ++bj) { const int col = u.pn * 256 + bj * 128 + wc * 32 + 8 * fq;
;                     const f32x4 a0 = *(const f32x4*)(xi + col) + acc[ai][bj][m][0], a1 = *(const f32x4*)(xi + col + 4) + acc[ai][bj][m][1];
;                     *(f32x4*)(xout + (size_t)row * DM + col) = a0; *(f32x4*)(xout + (size_t)row * DM + col + 4) = a1;
;                     u32x4 w; w.x = pk(a0[0], a0[1]); w.y = pk(a0[2], a0[3]); w.z = pk(a1[0], a1[1]); w.w = pk(a1[2], a1[3]);
;                     *(u32x4*)(xb + (size_t)row * DM + col) = w;
;                     sq += dot4(a0) + dot4(a1); }
;                 sq += __shfl_xor(sq, 16); sq += __shfl_xor(sq, 32);
;                 if (fq == 0) atomicAdd(ssout + row, sq);
.LBB0_2012:
	s_cmp_lt_u32 s58, 64
	s_cselect_b32 s98, s16, s8
	s_cselect_b32 s99, s17, s9
	s_cselect_b32 s100, 0, 0x4000
	v_lshl_add_u32 v138, s58, 8, v163
	v_lshl_or_b32 v175, s57, 8, v165
	v_lshlrev_b32_e32 v233, 2, v138
	v_lshlrev_b32_e32 v232, 1, v175
	v_lshl_add_u32 v234, v138, 11, v232
	v_lshlrev_b32_e32 v232, 2, v175
	v_lshl_add_u32 v235, v138, 12, v232
	v_subrev_u32_e32 v138, s100, v138
	v_lshl_add_u32 v236, v138, 12, v232
	global_load_dwordx4 v[148:151], v236, s[98:99]
	global_load_dwordx4 v[152:155], v236, s[98:99] offset:16
	global_load_dwordx4 v[176:179], v236, s[98:99] offset:512
	global_load_dwordx4 v[180:183], v236, s[98:99] offset:528
	v_add_u32_e32 v237, 0x10000, v236
	global_load_dwordx4 v[184:187], v237, s[98:99]
	global_load_dwordx4 v[188:191], v237, s[98:99] offset:16
	global_load_dwordx4 v[192:195], v237, s[98:99] offset:512
	global_load_dwordx4 v[196:199], v237, s[98:99] offset:528
	v_add_u32_e32 v237, 0x20000, v236
	global_load_dwordx4 v[200:203], v237, s[98:99]
	global_load_dwordx4 v[204:207], v237, s[98:99] offset:16
	global_load_dwordx4 v[208:211], v237, s[98:99] offset:512
	global_load_dwordx4 v[212:215], v237, s[98:99] offset:528
	v_add_u32_e32 v237, 0x30000, v236
	global_load_dwordx4 v[216:219], v237, s[98:99]
	global_load_dwordx4 v[220:223], v237, s[98:99] offset:16
	global_load_dwordx4 v[224:227], v237, s[98:99] offset:512
	global_load_dwordx4 v[228:231], v237, s[98:99] offset:528
	s_waitcnt vmcnt(12)
	v_pk_add_f32 v[126:127], v[126:127], v[148:149]
	v_pk_add_f32 v[128:129], v[128:129], v[150:151]
	v_pk_add_f32 v[122:123], v[122:123], v[152:153]
	v_pk_add_f32 v[124:125], v[124:125], v[154:155]
	v_pk_add_f32 v[118:119], v[118:119], v[176:177]
	v_pk_add_f32 v[120:121], v[120:121], v[178:179]
	v_pk_add_f32 v[114:115], v[114:115], v[180:181]
	v_pk_add_f32 v[116:117], v[116:117], v[182:183]
	global_store_dwordx4 v235, v[126:129], s[16:17]
	global_store_dwordx4 v235, v[122:125], s[16:17] offset:16
	global_store_dwordx4 v235, v[118:121], s[16:17] offset:512
	global_store_dwordx4 v235, v[114:117], s[16:17] offset:528
	v_mul_f32_e32 v176, v127, v127
	v_mul_f32_e32 v177, v129, v129
	v_mul_f32_e32 v178, v123, v123
	v_mul_f32_e32 v179, v125, v125
	v_fmac_f32_e32 v176, v126, v126
	v_fmac_f32_e32 v177, v128, v128
	v_fmac_f32_e32 v178, v122, v122
	v_fmac_f32_e32 v179, v124, v124
	v_add_f32_e32 v176, v176, v177
	v_add_f32_e32 v178, v178, v179
	v_add_f32_e32 v239, v176, v178
	v_mul_f32_e32 v176, v119, v119
	v_mul_f32_e32 v177, v121, v121
	v_mul_f32_e32 v178, v115, v115
	v_mul_f32_e32 v179, v117, v117
	v_fmac_f32_e32 v176, v118, v118
	v_fmac_f32_e32 v177, v120, v120
	v_fmac_f32_e32 v178, v114, v114
	v_fmac_f32_e32 v179, v116, v116
	v_add_f32_e32 v176, v176, v177
	v_add_f32_e32 v178, v178, v179
	v_add_f32_e32 v176, v176, v178
	v_add_f32_e32 v239, v239, v176
	v_mov_b32_e32 v240, v239
	s_nop 1
	v_permlane16_swap_b32_e32 v239, v240
	v_add_f32_e32 v239, v239, v240
	v_mov_b32_e32 v240, v239
	s_nop 1
	v_permlane32_swap_b32_e32 v239, v240
	v_add_f32_e32 v239, v239, v240
	s_mov_b64 exec, s[0:1]
	global_atomic_add_f32 v233, v239, s[10:11]
	s_mov_b64 exec, -1
	v_add_u32_e32 v237, 0x80000, v236
	global_load_dwordx4 v[148:151], v237, s[98:99]
	global_load_dwordx4 v[152:155], v237, s[98:99] offset:16
	global_load_dwordx4 v[176:179], v237, s[98:99] offset:512
	global_load_dwordx4 v[180:183], v237, s[98:99] offset:528
	s_waitcnt vmcnt(12)
	v_pk_add_f32 v[110:111], v[110:111], v[184:185]
	v_pk_add_f32 v[112:113], v[112:113], v[186:187]
	v_pk_add_f32 v[106:107], v[106:107], v[188:189]
	v_pk_add_f32 v[108:109], v[108:109], v[190:191]
	v_pk_add_f32 v[102:103], v[102:103], v[192:193]
	v_pk_add_f32 v[104:105], v[104:105], v[194:195]
	v_pk_add_f32 v[98:99], v[98:99], v[196:197]
	v_pk_add_f32 v[100:101], v[100:101], v[198:199]
	v_add_u32_e32 v238, 0x10000, v235
	global_store_dwordx4 v238, v[110:113], s[16:17]
	global_store_dwordx4 v238, v[106:109], s[16:17] offset:16
	global_store_dwordx4 v238, v[102:105], s[16:17] offset:512
	global_store_dwordx4 v238, v[98:101], s[16:17] offset:528
	v_mul_f32_e32 v192, v111, v111
	v_mul_f32_e32 v193, v113, v113
	v_mul_f32_e32 v194, v107, v107
	v_mul_f32_e32 v195, v109, v109
	v_fmac_f32_e32 v192, v110, v110
	v_fmac_f32_e32 v193, v112, v112
	v_fmac_f32_e32 v194, v106, v106
	v_fmac_f32_e32 v195, v108, v108
	v_add_f32_e32 v192, v192, v193
	v_add_f32_e32 v194, v194, v195
	v_add_f32_e32 v239, v192, v194
	v_mul_f32_e32 v192, v103, v103
	v_mul_f32_e32 v193, v105, v105
	v_mul_f32_e32 v194, v99, v99
	v_mul_f32_e32 v195, v101, v101
	v_fmac_f32_e32 v192, v102, v102
	v_fmac_f32_e32 v193, v104, v104
	v_fmac_f32_e32 v194, v98, v98
	v_fmac_f32_e32 v195, v100, v100
	v_add_f32_e32 v192, v192, v193
	v_add_f32_e32 v194, v194, v195
	v_add_f32_e32 v192, v192, v194
	v_add_f32_e32 v239, v239, v192
	v_mov_b32_e32 v240, v239
	s_nop 1
	v_permlane16_swap_b32_e32 v239, v240
	v_add_f32_e32 v239, v239, v240
	v_mov_b32_e32 v240, v239
	s_nop 1
	v_permlane32_swap_b32_e32 v239, v240
	v_add_f32_e32 v239, v239, v240
	s_mov_b64 exec, s[0:1]
	global_atomic_add_f32 v233, v239, s[10:11] offset:64
	s_mov_b64 exec, -1
	v_add_u32_e32 v237, 0x90000, v236
	global_load_dwordx4 v[184:187], v237, s[98:99]
	global_load_dwordx4 v[188:191], v237, s[98:99] offset:16
	global_load_dwordx4 v[192:195], v237, s[98:99] offset:512
	global_load_dwordx4 v[196:199], v237, s[98:99] offset:528
	s_waitcnt vmcnt(12)
; __device__ __forceinline__ unsigned pk(float lo, float hi) { return pg8::cvt_pk_bf16(lo, hi); }
; __device__ __forceinline__ float dot4(f32x4 v) { return (v[0] * v[0] + v[1] * v[1]) + (v[2] * v[2] + v[3] * v[3]); }
;     __device__ __forceinline__ void operator()(const pg8::f32x4 (&acc)[2][2][4][2], const pg8::Unit& u, int wr, int wc, int fr, int fq) const {
;     ...
;             for (int m = 0; m < 4; ++m) {
;                 const int row = row0 + ai * 128 + m * 16;
;                 const float* xi = (row < MP) ? xin_p + (size_t)row * DM : xin_s + (size_t)(row - MP) * DM;
;                 float sq = 0.f;
; #pragma unroll
;                 for (int bj = 0; bj < 2; ++bj) { const int col = u.pn * 256 + bj * 128 + wc * 32 + 8 * fq;
;                     const f32x4 a0 = *(const f32x4*)(xi + col) + acc[ai][bj][m][0], a1 = *(const f32x4*)(xi + col + 4) + acc[ai][bj][m][1];
;                     *(f32x4*)(xout + (size_t)row * DM + col) = a0; *(f32x4*)(xout + (size_t)row * DM + col + 4) = a1;
;                     u32x4 w; w.x = pk(a0[0], a0[1]); w.y = pk(a0[2], a0[3]); w.z = pk(a1[0], a1[1]); w.w = pk(a1[2], a1[3]);
;                     *(u32x4*)(xb + (size_t)row * DM + col) = w;
;                     sq += dot4(a0) + dot4(a1); }
;                 sq += __shfl_xor(sq, 16); sq += __shfl_xor(sq, 32);
;                 if (fq == 0) atomicAdd(ssout + row, sq);
	v_pk_add_f32 v[94:95], v[94:95], v[200:201]
	v_pk_add_f32 v[96:97], v[96:97], v[202:203]
	v_pk_add_f32 v[90:91], v[90:91], v[204:205]
	v_pk_add_f32 v[92:93], v[92:93], v[206:207]
	v_pk_add_f32 v[86:87], v[86:87], v[208:209]
	v_pk_add_f32 v[88:89], v[88:89], v[210:211]
	v_pk_add_f32 v[82:83], v[82:83], v[212:213]
	v_pk_add_f32 v[84:85], v[84:85], v[214:215]
	v_add_u32_e32 v238, 0x20000, v235
	global_store_dwordx4 v238, v[94:97], s[16:17]
	global_store_dwordx4 v238, v[90:93], s[16:17] offset:16
	global_store_dwordx4 v238, v[86:89], s[16:17] offset:512
	global_store_dwordx4 v238, v[82:85], s[16:17] offset:528
	v_mul_f32_e32 v208, v95, v95
	v_mul_f32_e32 v209, v97, v97
	v_mul_f32_e32 v210, v91, v91
	v_mul_f32_e32 v211, v93, v93
	v_fmac_f32_e32 v208, v94, v94
	v_fmac_f32_e32 v209, v96, v96
	v_fmac_f32_e32 v210, v90, v90
	v_fmac_f32_e32 v211, v92, v92
	v_add_f32_e32 v208, v208, v209
	v_add_f32_e32 v210, v210, v211
	v_add_f32_e32 v239, v208, v210
	v_mul_f32_e32 v208, v87, v87
	v_mul_f32_e32 v209, v89, v89
	v_mul_f32_e32 v210, v83, v83
	v_mul_f32_e32 v211, v85, v85
	v_fmac_f32_e32 v208, v86, v86
	v_fmac_f32_e32 v209, v88, v88
	v_fmac_f32_e32 v210, v82, v82
	v_fmac_f32_e32 v211, v84, v84
	v_add_f32_e32 v208, v208, v209
	v_add_f32_e32 v210, v210, v211
	v_add_f32_e32 v208, v208, v210
	v_add_f32_e32 v239, v239, v208
	v_mov_b32_e32 v240, v239
	s_nop 1
	v_permlane16_swap_b32_e32 v239, v240
	v_add_f32_e32 v239, v239, v240
	v_mov_b32_e32 v240, v239
	s_nop 1
	v_permlane32_swap_b32_e32 v239, v240
	v_add_f32_e32 v239, v239, v240
	s_mov_b64 exec, s[0:1]
	global_atomic_add_f32 v233, v239, s[10:11] offset:128
	s_mov_b64 exec, -1
	v_add_u32_e32 v237, 0xa0000, v236
	global_load_dwordx4 v[200:203], v237, s[98:99]
	global_load_dwordx4 v[204:207], v237, s[98:99] offset:16
	global_load_dwordx4 v[208:211], v237, s[98:99] offset:512
	global_load_dwordx4 v[212:215], v237, s[98:99] offset:528
	s_waitcnt vmcnt(12)
	v_pk_add_f32 v[78:79], v[78:79], v[216:217]
	v_pk_add_f32 v[80:81], v[80:81], v[218:219]
	v_pk_add_f32 v[74:75], v[74:75], v[220:221]
	v_pk_add_f32 v[76:77], v[76:77], v[222:223]
	v_pk_add_f32 v[70:71], v[70:71], v[224:225]
	v_pk_add_f32 v[72:73], v[72:73], v[226:227]
	v_pk_add_f32 v[66:67], v[66:67], v[228:229]
	v_pk_add_f32 v[68:69], v[68:69], v[230:231]
	v_add_u32_e32 v238, 0x30000, v235
	global_store_dwordx4 v238, v[78:81], s[16:17]
	global_store_dwordx4 v238, v[74:77], s[16:17] offset:16
	global_store_dwordx4 v238, v[70:73], s[16:17] offset:512
	global_store_dwordx4 v238, v[66:69], s[16:17] offset:528
	v_mul_f32_e32 v224, v79, v79
	v_mul_f32_e32 v225, v81, v81
	v_mul_f32_e32 v226, v75, v75
	v_mul_f32_e32 v227, v77, v77
	v_fmac_f32_e32 v224, v78, v78
	v_fmac_f32_e32 v225, v80, v80
	v_fmac_f32_e32 v226, v74, v74
	v_fmac_f32_e32 v227, v76, v76
	v_add_f32_e32 v224, v224, v225
	v_add_f32_e32 v226, v226, v227
	v_add_f32_e32 v239, v224, v226
	v_mul_f32_e32 v224, v71, v71
	v_mul_f32_e32 v225, v73, v73
	v_mul_f32_e32 v226, v67, v67
	v_mul_f32_e32 v227, v69, v69
	v_fmac_f32_e32 v224, v70, v70
	v_fmac_f32_e32 v225, v72, v72
	v_fmac_f32_e32 v226, v66, v66
	v_fmac_f32_e32 v227, v68, v68
	v_add_f32_e32 v224, v224, v225
	v_add_f32_e32 v226, v226, v227
	v_add_f32_e32 v224, v224, v226
	v_add_f32_e32 v239, v239, v224
	v_mov_b32_e32 v240, v239
	s_nop 1
	v_permlane16_swap_b32_e32 v239, v240
	v_add_f32_e32 v239, v239, v240
	v_mov_b32_e32 v240, v239
	s_nop 1
	v_permlane32_swap_b32_e32 v239, v240
	v_add_f32_e32 v239, v239, v240
	s_mov_b64 exec, s[0:1]
	global_atomic_add_f32 v233, v239, s[10:11] offset:192
	s_mov_b64 exec, -1
	v_add_u32_e32 v237, 0xb0000, v236
	global_load_dwordx4 v[216:219], v237, s[98:99]
	global_load_dwordx4 v[220:223], v237, s[98:99] offset:16
	global_load_dwordx4 v[224:227], v237, s[98:99] offset:512
	global_load_dwordx4 v[228:231], v237, s[98:99] offset:528
	s_waitcnt vmcnt(12)
	v_pk_add_f32 v[62:63], v[62:63], v[148:149]
	v_pk_add_f32 v[64:65], v[64:65], v[150:151]
	v_pk_add_f32 v[58:59], v[58:59], v[152:153]
	v_pk_add_f32 v[60:61], v[60:61], v[154:155]
	v_pk_add_f32 v[54:55], v[54:55], v[176:177]
	v_pk_add_f32 v[56:57], v[56:57], v[178:179]
	v_pk_add_f32 v[50:51], v[50:51], v[180:181]
	v_pk_add_f32 v[52:53], v[52:53], v[182:183]
	v_add_u32_e32 v238, 0x80000, v235
	global_store_dwordx4 v238, v[62:65], s[16:17]
	global_store_dwordx4 v238, v[58:61], s[16:17] offset:16
	global_store_dwordx4 v238, v[54:57], s[16:17] offset:512
	global_store_dwordx4 v238, v[50:53], s[16:17] offset:528
	v_mul_f32_e32 v176, v63, v63
	v_mul_f32_e32 v177, v65, v65
	v_mul_f32_e32 v178, v59, v59
	v_mul_f32_e32 v179, v61, v61
	v_fmac_f32_e32 v176, v62, v62
	v_fmac_f32_e32 v177, v64, v64
	v_fmac_f32_e32 v178, v58, v58
	v_fmac_f32_e32 v179, v60, v60
	v_add_f32_e32 v176, v176, v177
	v_add_f32_e32 v178, v178, v179
	v_add_f32_e32 v239, v176, v178
	v_mul_f32_e32 v176, v55, v55
	v_mul_f32_e32 v177, v57, v57
	v_mul_f32_e32 v178, v51, v51
	v_mul_f32_e32 v179, v53, v53
	v_fmac_f32_e32 v176, v54, v54
	v_fmac_f32_e32 v177, v56, v56
	v_fmac_f32_e32 v178, v50, v50
	v_fmac_f32_e32 v179, v52, v52
	v_add_f32_e32 v176, v176, v177
	v_add_f32_e32 v178, v178, v179
	v_add_f32_e32 v176, v176, v178
	v_add_f32_e32 v239, v239, v176
	v_mov_b32_e32 v240, v239
	s_nop 1
	v_permlane16_swap_b32_e32 v239, v240
	v_add_f32_e32 v239, v239, v240
	v_mov_b32_e32 v240, v239
	s_nop 1
	v_permlane32_swap_b32_e32 v239, v240
	v_add_f32_e32 v239, v239, v240
	s_mov_b64 exec, s[0:1]
	global_atomic_add_f32 v233, v239, s[10:11] offset:512
	s_mov_b64 exec, -1
	s_waitcnt vmcnt(8)
; #define PG8_BAR __builtin_amdgcn_s_barrier()
; __device__ __forceinline__ unsigned pk(float lo, float hi) { return pg8::cvt_pk_bf16(lo, hi); }
; __device__ __forceinline__ float dot4(f32x4 v) { return (v[0] * v[0] + v[1] * v[1]) + (v[2] * v[2] + v[3] * v[3]); }
; template <class Epi, class Sched, bool ALIGN_EPI = false, bool SP2 = false>
; __device__ __forceinline__ void gemm_phase(PG8_LAS unsigned char* lds, const Gemm g, const Sched& S, const Epi& E) {
;     ...
;         if (!has_next) break;
; #pragma unroll
;         for (int a = 0; a < 2; ++a)
; #pragma unroll
;             for (int b = 0; b < 2; ++b)
; #pragma unroll
;                 for (int m = 0; m < 4; ++m)
; #pragma unroll
;                     for (int n = 0; n < 2; ++n) acc[a][b][m][n] = (f32x4){0.f, 0.f, 0.f, 0.f};
;         cur = nxt; cA = nA; cB = nB; ++ui;
;         if constexpr (ALIGN_EPI) { if (wr == 1) PG8_BAR; }
;     }
;     __device__ __forceinline__ void operator()(const pg8::f32x4 (&acc)[2][2][4][2], const pg8::Unit& u, int wr, int wc, int fr, int fq) const {
;     ...
;             for (int m = 0; m < 4; ++m) {
;                 const int row = row0 + ai * 128 + m * 16;
;                 const float* xi = (row < MP) ? xin_p + (size_t)row * DM : xin_s + (size_t)(row - MP) * DM;
;                 float sq = 0.f;
; #pragma unroll
;                 for (int bj = 0; bj < 2; ++bj) { const int col = u.pn * 256 + bj * 128 + wc * 32 + 8 * fq;
;                     const f32x4 a0 = *(const f32x4*)(xi + col) + acc[ai][bj][m][0], a1 = *(const f32x4*)(xi + col + 4) + acc[ai][bj][m][1];
;                     *(f32x4*)(xout + (size_t)row * DM + col) = a0; *(f32x4*)(xout + (size_t)row * DM + col + 4) = a1;
;                     u32x4 w; w.x = pk(a0[0], a0[1]); w.y = pk(a0[2], a0[3]); w.z = pk(a1[0], a1[1]); w.w = pk(a1[2], a1[3]);
;                     *(u32x4*)(xb + (size_t)row * DM + col) = w;
;                     sq += dot4(a0) + dot4(a1); }
;                 sq += __shfl_xor(sq, 16); sq += __shfl_xor(sq, 32);
;                 if (fq == 0) atomicAdd(ssout + row, sq);
;             }
;     }
	v_pk_add_f32 v[46:47], v[46:47], v[184:185]
	v_pk_add_f32 v[48:49], v[48:49], v[186:187]
	v_pk_add_f32 v[42:43], v[42:43], v[188:189]
	v_pk_add_f32 v[44:45], v[44:45], v[190:191]
	v_pk_add_f32 v[38:39], v[38:39], v[192:193]
	v_pk_add_f32 v[40:41], v[40:41], v[194:195]
	v_pk_add_f32 v[34:35], v[34:35], v[196:197]
	v_pk_add_f32 v[36:37], v[36:37], v[198:199]
	v_add_u32_e32 v238, 0x90000, v235
	global_store_dwordx4 v238, v[46:49], s[16:17]
	global_store_dwordx4 v238, v[42:45], s[16:17] offset:16
	global_store_dwordx4 v238, v[38:41], s[16:17] offset:512
	global_store_dwordx4 v238, v[34:37], s[16:17] offset:528
	v_mul_f32_e32 v192, v47, v47
	v_mul_f32_e32 v193, v49, v49
	v_mul_f32_e32 v194, v43, v43
	v_mul_f32_e32 v195, v45, v45
	v_fmac_f32_e32 v192, v46, v46
	v_fmac_f32_e32 v193, v48, v48
	v_fmac_f32_e32 v194, v42, v42
	v_fmac_f32_e32 v195, v44, v44
	v_add_f32_e32 v192, v192, v193
	v_add_f32_e32 v194, v194, v195
	v_add_f32_e32 v239, v192, v194
	v_mul_f32_e32 v192, v39, v39
	v_mul_f32_e32 v193, v41, v41
	v_mul_f32_e32 v194, v35, v35
	v_mul_f32_e32 v195, v37, v37
	v_fmac_f32_e32 v192, v38, v38
	v_fmac_f32_e32 v193, v40, v40
	v_fmac_f32_e32 v194, v34, v34
	v_fmac_f32_e32 v195, v36, v36
	v_add_f32_e32 v192, v192, v193
	v_add_f32_e32 v194, v194, v195
	v_add_f32_e32 v192, v192, v194
	v_add_f32_e32 v239, v239, v192
	v_mov_b32_e32 v240, v239
	s_nop 1
	v_permlane16_swap_b32_e32 v239, v240
	v_add_f32_e32 v239, v239, v240
	v_mov_b32_e32 v240, v239
	s_nop 1
	v_permlane32_swap_b32_e32 v239, v240
	v_add_f32_e32 v239, v239, v240
	s_mov_b64 exec, s[0:1]
	global_atomic_add_f32 v233, v239, s[10:11] offset:576
	s_mov_b64 exec, -1
	s_waitcnt vmcnt(4)
	v_pk_add_f32 v[30:31], v[30:31], v[200:201]
	v_pk_add_f32 v[32:33], v[32:33], v[202:203]
	v_pk_add_f32 v[26:27], v[26:27], v[204:205]
	v_pk_add_f32 v[28:29], v[28:29], v[206:207]
	v_pk_add_f32 v[22:23], v[22:23], v[208:209]
	v_pk_add_f32 v[24:25], v[24:25], v[210:211]
	v_pk_add_f32 v[18:19], v[18:19], v[212:213]
	v_pk_add_f32 v[20:21], v[20:21], v[214:215]
	v_add_u32_e32 v238, 0xa0000, v235
	global_store_dwordx4 v238, v[30:33], s[16:17]
	global_store_dwordx4 v238, v[26:29], s[16:17] offset:16
	global_store_dwordx4 v238, v[22:25], s[16:17] offset:512
	global_store_dwordx4 v238, v[18:21], s[16:17] offset:528
	v_mul_f32_e32 v208, v31, v31
	v_mul_f32_e32 v209, v33, v33
	v_mul_f32_e32 v210, v27, v27
	v_mul_f32_e32 v211, v29, v29
	v_fmac_f32_e32 v208, v30, v30
	v_fmac_f32_e32 v209, v32, v32
	v_fmac_f32_e32 v210, v26, v26
	v_fmac_f32_e32 v211, v28, v28
	v_add_f32_e32 v208, v208, v209
	v_add_f32_e32 v210, v210, v211
	v_add_f32_e32 v239, v208, v210
	v_mul_f32_e32 v208, v23, v23
	v_mul_f32_e32 v209, v25, v25
	v_mul_f32_e32 v210, v19, v19
	v_mul_f32_e32 v211, v21, v21
	v_fmac_f32_e32 v208, v22, v22
	v_fmac_f32_e32 v209, v24, v24
	v_fmac_f32_e32 v210, v18, v18
	v_fmac_f32_e32 v211, v20, v20
	v_add_f32_e32 v208, v208, v209
	v_add_f32_e32 v210, v210, v211
	v_add_f32_e32 v208, v208, v210
	v_add_f32_e32 v239, v239, v208
	v_mov_b32_e32 v240, v239
	s_nop 1
	v_permlane16_swap_b32_e32 v239, v240
	v_add_f32_e32 v239, v239, v240
	v_mov_b32_e32 v240, v239
	s_nop 1
	v_permlane32_swap_b32_e32 v239, v240
	v_add_f32_e32 v239, v239, v240
	s_mov_b64 exec, s[0:1]
	global_atomic_add_f32 v233, v239, s[10:11] offset:640
	s_mov_b64 exec, -1
	s_waitcnt vmcnt(0)
	v_pk_add_f32 v[14:15], v[14:15], v[216:217]
	v_pk_add_f32 v[16:17], v[16:17], v[218:219]
	v_pk_add_f32 v[10:11], v[10:11], v[220:221]
	v_pk_add_f32 v[12:13], v[12:13], v[222:223]
	v_pk_add_f32 v[6:7], v[6:7], v[224:225]
	v_pk_add_f32 v[8:9], v[8:9], v[226:227]
	v_pk_add_f32 v[2:3], v[2:3], v[228:229]
	v_pk_add_f32 v[4:5], v[4:5], v[230:231]
	v_add_u32_e32 v238, 0xb0000, v235
	global_store_dwordx4 v238, v[14:17], s[16:17]
	global_store_dwordx4 v238, v[10:13], s[16:17] offset:16
	global_store_dwordx4 v238, v[6:9], s[16:17] offset:512
	global_store_dwordx4 v238, v[2:5], s[16:17] offset:528
	v_mul_f32_e32 v224, v15, v15
	v_mul_f32_e32 v225, v17, v17
	v_mul_f32_e32 v226, v11, v11
	v_mul_f32_e32 v227, v13, v13
	v_fmac_f32_e32 v224, v14, v14
	v_fmac_f32_e32 v225, v16, v16
	v_fmac_f32_e32 v226, v10, v10
	v_fmac_f32_e32 v227, v12, v12
	v_add_f32_e32 v224, v224, v225
	v_add_f32_e32 v226, v226, v227
	v_add_f32_e32 v239, v224, v226
	v_mul_f32_e32 v224, v7, v7
	v_mul_f32_e32 v225, v9, v9
	v_mul_f32_e32 v226, v3, v3
	v_mul_f32_e32 v227, v5, v5
	v_fmac_f32_e32 v224, v6, v6
	v_fmac_f32_e32 v225, v8, v8
	v_fmac_f32_e32 v226, v2, v2
	v_fmac_f32_e32 v227, v4, v4
	v_add_f32_e32 v224, v224, v225
	v_add_f32_e32 v226, v226, v227
	v_add_f32_e32 v224, v224, v226
	v_add_f32_e32 v239, v239, v224
	v_mov_b32_e32 v240, v239
	s_nop 1
	v_permlane16_swap_b32_e32 v239, v240
	v_add_f32_e32 v239, v239, v240
	v_mov_b32_e32 v240, v239
	s_nop 1
	v_permlane32_swap_b32_e32 v239, v240
	v_add_f32_e32 v239, v239, v240
	s_mov_b64 exec, s[0:1]
	global_atomic_add_f32 v233, v239, s[10:11] offset:704
	s_mov_b64 exec, -1
	s_and_b64 vcc, exec, s[4:5]
	s_mov_b64 s[4:5], -1
	s_cbranch_vccnz .LBB0_2001
	s_andn2_b64 vcc, exec, s[14:15]
	s_cbranch_vccnz .LBB0_2000
	s_barrier
	s_branch .LBB0_2000
